# v6_widen_p7_stores
# speedup vs baseline: 1.0222x; 1.0074x over previous
; #define LAS __attribute__((address_space(3)))
; DI void attn_prompt_item(const Params& p, int item, ldsp lds, int tid_) {
;     ...
;   const size_t qrow = (size_t)b * 2048 + qt * 256 + wid * 32 + l31;
;   bf16x8 qreg[8];
; #pragma unroll
;   for (int s = 0; s < 8; ++s) qreg[s] = *(const bf16x8*)(qx + qrow * D + h * 256 + 16 * s + 8 * h2);
; #pragma unroll
;   for (int hb = 0; hb < 2; ++hb) {
;     u32x4 kp[8];
; #pragma unroll
;     for (int i = 0; i < 8; ++i) { const int idx = tid + 512 * (hb * 8 + i), key = idx >> 5, c = idx & 31; kp[i] = ld16(mkb + (size_t)(b * 256 + key) * D + h * 256 + c * 8); }
; #pragma unroll
;     for (int i = 0; i < 8; ++i) { const int idx = tid + 512 * (hb * 8 + i), key = idx >> 5, c = idx & 31; *(LAS u32x4*)(lds + key * 512 + ((c ^ (key & 15)) * 16)) = kp[i]; }
;   }
.LBB0_1672:
	v_mov_b32_e32 v68, v212
	s_ashr_i32 s28, s45, 5
	s_ashr_i32 s29, s28, 31
	v_readfirstlane_b32 s3, v68
	s_lshl_b64 s[46:47], s[28:29], 11
	s_and_b32 s26, s33, 0x700
	s_ashr_i32 s3, s3, 1
	v_and_b32_e32 v69, 31, v68
	s_or_b32 s26, s46, s26
	s_and_b32 s48, s3, 0xffffffe0
	s_ashr_i32 s49, s48, 31
	v_or_b32_e32 v0, s26, v69
	v_mov_b32_e32 v1, s47
	s_and_b32 s3, s30, 0x300
	v_add_u32_e32 v6, 0x200, v68
	v_lshl_add_u64 v[0:1], v[0:1], 0, s[48:49]
	s_lshl_b32 s26, s3, 1
	s_lshl_b32 s29, s28, 8
	v_ashrrev_i32_e32 v176, 5, v68
	v_ashrrev_i32_e32 v177, 5, v6
	v_lshlrev_b64 v[162:163], 11, v[0:1]
	s_add_u32 s46, s0, s26
	v_lshlrev_b32_e32 v174, 4, v68
	v_add_u32_e32 v4, s29, v176
	v_add_u32_e32 v6, s29, v177
	v_bfe_u32 v208, v68, 5, 1
	v_lshl_add_u64 v[0:1], s[4:5], 0, v[162:163]
	s_addc_u32 s47, s1, 0
	v_and_b32_e32 v164, 0x1f0, v174
	v_mov_b32_e32 v165, v161
	v_ashrrev_i32_e32 v5, 31, v4
	v_ashrrev_i32_e32 v7, 31, v6
	v_lshl_add_u64 v[0:1], v[0:1], 0, s[26:27]
	v_lshlrev_b32_e32 v2, 4, v208
	v_mov_b32_e32 v3, v161
	v_lshl_add_u64 v[64:65], s[46:47], 0, v[164:165]
	v_lshlrev_b64 v[4:5], 11, v[4:5]
	v_lshlrev_b64 v[6:7], 11, v[6:7]
	v_lshl_add_u64 v[166:167], v[0:1], 0, v[2:3]
	v_lshl_add_u64 v[4:5], v[64:65], 0, v[4:5]
	v_lshl_add_u64 v[8:9], v[64:65], 0, v[6:7]
	global_load_dwordx4 v[0:3], v[166:167], off
	global_load_dwordx4 v[152:155], v[166:167], off offset:32
	global_load_dwordx4 v[148:151], v[166:167], off offset:64
	global_load_dwordx4 v[144:147], v[166:167], off offset:96
	global_load_dwordx4 v[140:143], v[166:167], off offset:128
	global_load_dwordx4 v[136:139], v[166:167], off offset:160
	global_load_dwordx4 v[132:135], v[166:167], off offset:192
	global_load_dwordx4 v[128:131], v[166:167], off offset:224
	s_nop 0
	global_load_dwordx4 v[4:7], v[4:5], off
	s_nop 0
	global_load_dwordx4 v[8:11], v[8:9], off
	v_add_u32_e32 v12, 0x400, v68
	v_add_u32_e32 v14, 0x600, v68
	v_add_u32_e32 v20, 0x800, v68
	v_add_u32_e32 v22, 0xa00, v68
	v_ashrrev_i32_e32 v178, 5, v12
	v_ashrrev_i32_e32 v180, 5, v14
	v_ashrrev_i32_e32 v181, 5, v20
	v_ashrrev_i32_e32 v183, 5, v22
	v_add_u32_e32 v28, 0xc00, v68
	v_add_u32_e32 v30, 0xe00, v68
	v_add_u32_e32 v36, 0x1000, v68
	v_add_u32_e32 v38, 0x1200, v68
	v_add_u32_e32 v44, 0x1400, v68
	v_add_u32_e32 v46, 0x1600, v68
	v_add_u32_e32 v52, 0x1800, v68
	v_add_u32_e32 v54, 0x1a00, v68
	v_add_u32_e32 v60, 0x1c00, v68
	v_add_u32_e32 v66, 0x1e00, v68
	v_add_u32_e32 v12, s29, v178
	v_add_u32_e32 v14, s29, v180
	v_add_u32_e32 v20, s29, v181
	v_add_u32_e32 v22, s29, v183
	v_ashrrev_i32_e32 v184, 5, v28
	v_ashrrev_i32_e32 v186, 5, v30
	v_ashrrev_i32_e32 v195, 5, v36
	v_ashrrev_i32_e32 v197, 5, v38
	v_ashrrev_i32_e32 v199, 5, v44
	v_ashrrev_i32_e32 v201, 5, v46
	v_ashrrev_i32_e32 v203, 5, v52
	v_ashrrev_i32_e32 v204, 5, v54
	v_ashrrev_i32_e32 v206, 5, v60
	v_ashrrev_i32_e32 v207, 5, v66
	v_ashrrev_i32_e32 v13, 31, v12
	v_ashrrev_i32_e32 v15, 31, v14
	v_ashrrev_i32_e32 v21, 31, v20
	v_ashrrev_i32_e32 v23, 31, v22
	v_add_u32_e32 v28, s29, v184
	v_add_u32_e32 v30, s29, v186
	v_add_u32_e32 v36, s29, v195
	v_add_u32_e32 v38, s29, v197
	v_add_u32_e32 v44, s29, v199
	v_add_u32_e32 v46, s29, v201
	v_add_u32_e32 v52, s29, v203
	v_add_u32_e32 v54, s29, v204
	v_add_u32_e32 v60, s29, v206
	v_add_u32_e32 v66, s29, v207
	v_lshlrev_b64 v[12:13], 11, v[12:13]
	v_lshlrev_b64 v[14:15], 11, v[14:15]
	v_lshlrev_b64 v[20:21], 11, v[20:21]
	v_lshlrev_b64 v[22:23], 11, v[22:23]
	v_ashrrev_i32_e32 v29, 31, v28
	v_ashrrev_i32_e32 v31, 31, v30
	v_ashrrev_i32_e32 v37, 31, v36
	v_ashrrev_i32_e32 v39, 31, v38
	v_ashrrev_i32_e32 v45, 31, v44
	v_ashrrev_i32_e32 v47, 31, v46
	v_ashrrev_i32_e32 v53, 31, v52
	v_ashrrev_i32_e32 v55, 31, v54
	v_ashrrev_i32_e32 v61, 31, v60
	v_ashrrev_i32_e32 v67, 31, v66
	v_lshl_add_u64 v[12:13], v[64:65], 0, v[12:13]
	v_lshl_add_u64 v[16:17], v[64:65], 0, v[14:15]
	v_lshl_add_u64 v[20:21], v[64:65], 0, v[20:21]
	v_lshl_add_u64 v[24:25], v[64:65], 0, v[22:23]
	v_lshlrev_b64 v[28:29], 11, v[28:29]
	v_lshlrev_b64 v[30:31], 11, v[30:31]
	v_lshlrev_b64 v[36:37], 11, v[36:37]
	v_lshlrev_b64 v[38:39], 11, v[38:39]
	v_lshlrev_b64 v[44:45], 11, v[44:45]
	v_lshlrev_b64 v[46:47], 11, v[46:47]
	v_lshlrev_b64 v[52:53], 11, v[52:53]
	v_lshlrev_b64 v[54:55], 11, v[54:55]
	v_lshlrev_b64 v[60:61], 11, v[60:61]
	v_lshlrev_b64 v[66:67], 11, v[66:67]
	global_load_dwordx4 v[12:15], v[12:13], off
	s_nop 0
	global_load_dwordx4 v[16:19], v[16:17], off
	s_nop 0
	global_load_dwordx4 v[20:23], v[20:21], off
	s_nop 0
	global_load_dwordx4 v[24:27], v[24:25], off
	v_lshl_add_u64 v[28:29], v[64:65], 0, v[28:29]
	v_lshl_add_u64 v[32:33], v[64:65], 0, v[30:31]
	v_lshl_add_u64 v[36:37], v[64:65], 0, v[36:37]
	v_lshl_add_u64 v[40:41], v[64:65], 0, v[38:39]
	v_lshl_add_u64 v[44:45], v[64:65], 0, v[44:45]
	v_lshl_add_u64 v[48:49], v[64:65], 0, v[46:47]
	v_lshl_add_u64 v[52:53], v[64:65], 0, v[52:53]
	v_lshl_add_u64 v[56:57], v[64:65], 0, v[54:55]
	v_lshl_add_u64 v[60:61], v[64:65], 0, v[60:61]
	v_lshl_add_u64 v[64:65], v[64:65], 0, v[66:67]
	global_load_dwordx4 v[28:31], v[28:29], off
	s_nop 0
	global_load_dwordx4 v[32:35], v[32:33], off
	s_nop 0
	global_load_dwordx4 v[36:39], v[36:37], off
	s_nop 0
	global_load_dwordx4 v[40:43], v[40:41], off
	s_nop 0
	global_load_dwordx4 v[44:47], v[44:45], off
	s_nop 0
	global_load_dwordx4 v[48:51], v[48:49], off
	s_nop 0
	global_load_dwordx4 v[52:55], v[52:53], off
	s_nop 0
	global_load_dwordx4 v[56:59], v[56:57], off
	v_bitop3_b32 v72, v176, v69, 15 bitop3:0x6c
	global_load_dwordx4 v[60:63], v[60:61], off
	v_lshlrev_b32_e32 v71, 9, v176
	global_load_dwordx4 v[64:67], v[64:65], off
	v_lshlrev_b32_e32 v72, 4, v72
	v_add3_u32 v179, 16, v71, v72
	s_waitcnt vmcnt(15)
; #define LAS __attribute__((address_space(3)))
; DI void attn_prompt_item(const Params& p, int item, ldsp lds, int tid_) {
;     ...
;     for (int i = 0; i < 8; ++i) { const int idx = tid + 512 * (hb * 8 + i), key = idx >> 5, c = idx & 31; *(LAS u32x4*)(lds + key * 512 + ((c ^ (key & 15)) * 16)) = kp[i]; }
;   }
;   __syncthreads();
;   f32x16 S[8];
; #pragma unroll
;   for (int kt = 0; kt < 8; ++kt)
; #pragma unroll
;     for (int i = 0; i < 16; ++i) S[kt][i] = 0.f;
; #pragma unroll
;   for (int sh = 0; sh < 2; ++sh) {
;     if (sh == 1) {
;       __builtin_amdgcn_sched_barrier(0);
; #pragma unroll
;       for (int s = 0; s < 8; ++s) qreg[s] = *(const bf16x8*)(qx + qrow * D + h * 256 + 16 * (8 + s) + 8 * h2);
;     }
;     {
;       bf16x8 kfa[4], kfb[4];
;     ...
; #pragma unroll
;       for (int j = 0; j < 4; ++j) kfa[j] = *(const LAS bf16x8*)KF_ADDR(0, j);
; #pragma unroll
;       for (int gi = 0; gi < 16; ++gi) {
;         if (gi + 1 < 16) {
; #pragma unroll
;           for (int j = 0; j < 4; ++j) { if (gi & 1) kfa[j] = *(const LAS bf16x8*)KF_ADDR(gi + 1, j); else kfb[j] = *(const LAS bf16x8*)KF_ADDR(gi + 1, j); } }
; #pragma unroll
;         for (int j = 0; j < 4; ++j) S[gi >> 1] = __builtin_amdgcn_mfma_f32_32x32x16_bf16((gi & 1) ? kfb[j] : kfa[j], qreg[(gi & 1) * 4 + j], S[gi >> 1], 0, 0, 0);
;         __builtin_amdgcn_sched_barrier(0);
;       }
	ds_write_b128 v179, v[4:7]
	v_bitop3_b32 v5, v177, v69, 15 bitop3:0x6c
	v_lshlrev_b32_e32 v4, 9, v177
	v_lshlrev_b32_e32 v5, 4, v5
	v_add3_u32 v182, 16, v4, v5
	v_bitop3_b32 v5, v178, v69, 15 bitop3:0x6c
	v_lshlrev_b32_e32 v4, 9, v178
	v_lshlrev_b32_e32 v5, 4, v5
	v_add3_u32 v185, 16, v4, v5
	v_bitop3_b32 v5, v180, v69, 15 bitop3:0x6c
	v_lshlrev_b32_e32 v4, 9, v180
	v_lshlrev_b32_e32 v5, 4, v5
	v_add3_u32 v187, 16, v4, v5
	v_bitop3_b32 v5, v181, v69, 15 bitop3:0x6c
	v_lshlrev_b32_e32 v4, 9, v181
	v_lshlrev_b32_e32 v5, 4, v5
	v_add3_u32 v188, 16, v4, v5
	v_bitop3_b32 v5, v183, v69, 15 bitop3:0x6c
	v_lshlrev_b32_e32 v4, 9, v183
	v_lshlrev_b32_e32 v5, 4, v5
	v_add3_u32 v189, 16, v4, v5
	v_bitop3_b32 v5, v184, v69, 15 bitop3:0x6c
	v_lshlrev_b32_e32 v4, 9, v184
	v_lshlrev_b32_e32 v5, 4, v5
	v_add3_u32 v190, 16, v4, v5
	v_bitop3_b32 v5, v186, v69, 15 bitop3:0x6c
	v_lshlrev_b32_e32 v4, 9, v186
	v_lshlrev_b32_e32 v5, 4, v5
	v_add3_u32 v191, 16, v4, v5
	v_bitop3_b32 v5, v195, v69, 15 bitop3:0x6c
	v_lshlrev_b32_e32 v4, 9, v195
	v_lshlrev_b32_e32 v5, 4, v5
	v_add3_u32 v192, 16, v4, v5
	v_bitop3_b32 v5, v197, v69, 15 bitop3:0x6c
	v_lshlrev_b32_e32 v4, 9, v197
	v_lshlrev_b32_e32 v5, 4, v5
	v_add3_u32 v193, 16, v4, v5
	v_bitop3_b32 v5, v199, v69, 15 bitop3:0x6c
	v_lshlrev_b32_e32 v4, 9, v199
	v_lshlrev_b32_e32 v5, 4, v5
	v_add3_u32 v194, 16, v4, v5
	v_bitop3_b32 v5, v201, v69, 15 bitop3:0x6c
	v_lshlrev_b32_e32 v4, 9, v201
	v_lshlrev_b32_e32 v5, 4, v5
	v_add3_u32 v196, 16, v4, v5
	v_bitop3_b32 v5, v203, v69, 15 bitop3:0x6c
	v_lshlrev_b32_e32 v4, 9, v203
	v_lshlrev_b32_e32 v5, 4, v5
	v_add3_u32 v200, 16, v4, v5
	v_bitop3_b32 v5, v204, v69, 15 bitop3:0x6c
	v_lshlrev_b32_e32 v4, 9, v204
	v_lshlrev_b32_e32 v5, 4, v5
	v_add3_u32 v198, 16, v4, v5
	v_bitop3_b32 v5, v206, v69, 15 bitop3:0x6c
	v_lshlrev_b32_e32 v4, 9, v206
	v_lshlrev_b32_e32 v5, 4, v5
	v_add3_u32 v202, 16, v4, v5
	v_bitop3_b32 v5, v207, v69, 15 bitop3:0x6c
	v_lshrrev_b32_e32 v70, 5, v68
	v_lshlrev_b32_e32 v4, 9, v207
	v_lshlrev_b32_e32 v5, 4, v5
	v_and_b32_e32 v175, 15, v68
	v_add3_u32 v205, 16, v4, v5
	v_lshlrev_b32_e32 v172, 9, v69
	v_bitop3_b32 v4, v70, v175, 1 bitop3:0x6c
	v_add_u32_e32 v173, 16, v172
	v_lshlrev_b32_e32 v209, 4, v4
	s_waitcnt vmcnt(14)
	ds_write_b128 v182, v[8:11]
	s_waitcnt vmcnt(13)
	ds_write_b128 v185, v[12:15]
	s_waitcnt vmcnt(12)
	ds_write_b128 v187, v[16:19]
	s_waitcnt vmcnt(11)
	ds_write_b128 v188, v[20:23]
	s_waitcnt vmcnt(10)
	ds_write_b128 v189, v[24:27]
	v_add_u32_e32 v24, v173, v209
	s_waitcnt vmcnt(9)
	ds_write_b128 v190, v[28:31]
	s_waitcnt vmcnt(8)
	ds_write_b128 v191, v[32:35]
	s_waitcnt vmcnt(7)
	ds_write_b128 v192, v[36:39]
	s_waitcnt vmcnt(6)
	ds_write_b128 v193, v[40:43]
	s_waitcnt vmcnt(5)
	ds_write_b128 v194, v[44:47]
	s_waitcnt vmcnt(4)
	ds_write_b128 v196, v[48:51]
	s_waitcnt vmcnt(3)
	ds_write_b128 v200, v[52:55]
	s_waitcnt vmcnt(2)
	ds_write_b128 v198, v[56:59]
	s_waitcnt vmcnt(1)
	ds_write_b128 v202, v[60:63]
	s_waitcnt vmcnt(0)
	ds_write_b128 v205, v[64:67]
	s_waitcnt lgkmcnt(0)
	s_barrier
	ds_read_b128 v[4:7], v24
	v_bitop3_b32 v8, v208, v175, 2 bitop3:0x36
	v_lshlrev_b32_e32 v210, 4, v8
	v_add_u32_e32 v25, v173, v210
	ds_read_b128 v[8:11], v25
	s_waitcnt lgkmcnt(1)
	v_mfma_f32_32x32x16_bf16 v[112:127], v[4:7], v[0:3], 0
	v_bitop3_b32 v12, v208, v175, 4 bitop3:0x36
	v_lshlrev_b32_e32 v211, 4, v12
	v_bitop3_b32 v4, v208, v175, 6 bitop3:0x36
	v_add_u32_e32 v26, v173, v211
	v_lshlrev_b32_e32 v218, 4, v4
	v_add_u32_e32 v27, v173, v218
	ds_read_b128 v[4:7], v26
	ds_read_b128 v[12:15], v27
	s_waitcnt lgkmcnt(2)
	v_mfma_f32_32x32x16_bf16 v[112:127], v[8:11], v[152:155], v[112:127]
	v_bitop3_b32 v16, v208, v175, 8 bitop3:0x36
	v_bitop3_b32 v20, v208, v175, 12 bitop3:0x36
	v_lshlrev_b32_e32 v226, 4, v16
	v_bitop3_b32 v8, v208, v175, 10 bitop3:0x36
	v_lshlrev_b32_e32 v228, 4, v20
	v_add_u32_e32 v28, v173, v226
	v_lshlrev_b32_e32 v227, 4, v8
	s_waitcnt lgkmcnt(1)
	v_mfma_f32_32x32x16_bf16 v[112:127], v[4:7], v[148:151], v[112:127]
	v_bitop3_b32 v4, v208, v175, 14 bitop3:0x36
	v_add_u32_e32 v30, v173, v228
	v_lshlrev_b32_e32 v229, 4, v4
	v_add_u32_e32 v29, v173, v227
	ds_read_b128 v[8:11], v28
	ds_read_b128 v[16:19], v29
	v_add_u32_e32 v31, v173, v229
	ds_read_b128 v[4:7], v30
	ds_read_b128 v[20:23], v31
	v_lshlrev_b32_e32 v160, 3, v208
	s_waitcnt lgkmcnt(4)
	v_mfma_f32_32x32x16_bf16 v[112:127], v[12:15], v[144:147], v[112:127]
	s_waitcnt lgkmcnt(3)
	v_mfma_f32_32x32x16_bf16 v[112:127], v[8:11], v[140:143], v[112:127]
	s_waitcnt lgkmcnt(2)
	v_mfma_f32_32x32x16_bf16 v[112:127], v[16:19], v[136:139], v[112:127]
	s_waitcnt lgkmcnt(1)
	v_mfma_f32_32x32x16_bf16 v[112:127], v[4:7], v[132:135], v[112:127]
	ds_read_b128 v[4:7], v24 offset:16384
	ds_read_b128 v[8:11], v25 offset:16384
	ds_read_b128 v[12:15], v26 offset:16384
	ds_read_b128 v[16:19], v27 offset:16384
	s_waitcnt lgkmcnt(4)
	v_mfma_f32_32x32x16_bf16 v[112:127], v[20:23], v[128:131], v[112:127]
	s_waitcnt lgkmcnt(3)
	v_mfma_f32_32x32x16_bf16 v[96:111], v[4:7], v[0:3], 0
	s_waitcnt lgkmcnt(2)
	v_mfma_f32_32x32x16_bf16 v[96:111], v[8:11], v[152:155], v[96:111]
	s_waitcnt lgkmcnt(1)
	v_mfma_f32_32x32x16_bf16 v[96:111], v[12:15], v[148:151], v[96:111]
	ds_read_b128 v[4:7], v28 offset:16384
	ds_read_b128 v[8:11], v29 offset:16384
	ds_read_b128 v[12:15], v30 offset:16384
	ds_read_b128 v[20:23], v31 offset:16384
	s_waitcnt lgkmcnt(4)
	v_mfma_f32_32x32x16_bf16 v[96:111], v[16:19], v[144:147], v[96:111]
	s_waitcnt lgkmcnt(3)
	v_mfma_f32_32x32x16_bf16 v[96:111], v[4:7], v[140:143], v[96:111]
	s_waitcnt lgkmcnt(2)
	v_mfma_f32_32x32x16_bf16 v[96:111], v[8:11], v[136:139], v[96:111]
	s_waitcnt lgkmcnt(1)
; #define LAS __attribute__((address_space(3)))
; DI void attn_prompt_item(const Params& p, int item, ldsp lds, int tid_) {
;     ...
; #pragma unroll
;       for (int j = 0; j < 4; ++j) kfa[j] = *(const LAS bf16x8*)KF_ADDR(0, j);
; #pragma unroll
;       for (int gi = 0; gi < 16; ++gi) {
;         if (gi + 1 < 16) {
; #pragma unroll
;           for (int j = 0; j < 4; ++j) { if (gi & 1) kfa[j] = *(const LAS bf16x8*)KF_ADDR(gi + 1, j); else kfb[j] = *(const LAS bf16x8*)KF_ADDR(gi + 1, j); } }
; #pragma unroll
;         for (int j = 0; j < 4; ++j) S[gi >> 1] = __builtin_amdgcn_mfma_f32_32x32x16_bf16((gi & 1) ? kfb[j] : kfa[j], qreg[(gi & 1) * 4 + j], S[gi >> 1], 0, 0, 0);
;         __builtin_amdgcn_sched_barrier(0);
;       }
	v_mfma_f32_32x32x16_bf16 v[96:111], v[12:15], v[132:135], v[96:111]
	ds_read_b128 v[4:7], v24 offset:32768
	ds_read_b128 v[8:11], v25 offset:32768
	ds_read_b128 v[12:15], v26 offset:32768
	ds_read_b128 v[16:19], v27 offset:32768
	s_waitcnt lgkmcnt(4)
	v_mfma_f32_32x32x16_bf16 v[96:111], v[20:23], v[128:131], v[96:111]
	s_waitcnt lgkmcnt(3)
	v_mfma_f32_32x32x16_bf16 v[80:95], v[4:7], v[0:3], 0
	s_waitcnt lgkmcnt(2)
	v_mfma_f32_32x32x16_bf16 v[80:95], v[8:11], v[152:155], v[80:95]
	s_waitcnt lgkmcnt(1)
	v_mfma_f32_32x32x16_bf16 v[80:95], v[12:15], v[148:151], v[80:95]
	ds_read_b128 v[4:7], v28 offset:32768
	ds_read_b128 v[8:11], v29 offset:32768
	ds_read_b128 v[12:15], v30 offset:32768
	ds_read_b128 v[20:23], v31 offset:32768
	s_waitcnt lgkmcnt(4)
	v_mfma_f32_32x32x16_bf16 v[80:95], v[16:19], v[144:147], v[80:95]
	s_waitcnt lgkmcnt(3)
	v_mfma_f32_32x32x16_bf16 v[80:95], v[4:7], v[140:143], v[80:95]
	s_waitcnt lgkmcnt(2)
	v_mfma_f32_32x32x16_bf16 v[80:95], v[8:11], v[136:139], v[80:95]
	s_waitcnt lgkmcnt(1)
	v_mfma_f32_32x32x16_bf16 v[80:95], v[12:15], v[132:135], v[80:95]
	ds_read_b128 v[4:7], v24 offset:49152
	ds_read_b128 v[8:11], v25 offset:49152
	ds_read_b128 v[12:15], v26 offset:49152
	ds_read_b128 v[16:19], v27 offset:49152
	s_waitcnt lgkmcnt(4)
	v_mfma_f32_32x32x16_bf16 v[80:95], v[20:23], v[128:131], v[80:95]
	s_waitcnt lgkmcnt(3)
	v_mfma_f32_32x32x16_bf16 v[64:79], v[4:7], v[0:3], 0
	s_waitcnt lgkmcnt(2)
	v_mfma_f32_32x32x16_bf16 v[64:79], v[8:11], v[152:155], v[64:79]
	s_waitcnt lgkmcnt(1)
	v_mfma_f32_32x32x16_bf16 v[64:79], v[12:15], v[148:151], v[64:79]
	ds_read_b128 v[4:7], v28 offset:49152
	ds_read_b128 v[8:11], v29 offset:49152
	ds_read_b128 v[12:15], v30 offset:49152
	ds_read_b128 v[20:23], v31 offset:49152
	s_waitcnt lgkmcnt(4)
	v_mfma_f32_32x32x16_bf16 v[64:79], v[16:19], v[144:147], v[64:79]
	s_waitcnt lgkmcnt(3)
	v_mfma_f32_32x32x16_bf16 v[64:79], v[4:7], v[140:143], v[64:79]
	v_add_u32_e32 v230, 0x10000, v173
	v_add_u32_e32 v4, v230, v209
	v_add_u32_e32 v16, v230, v218
	s_waitcnt lgkmcnt(2)
	v_mfma_f32_32x32x16_bf16 v[64:79], v[8:11], v[136:139], v[64:79]
	v_add_u32_e32 v8, v230, v210
	ds_read_b128 v[4:7], v4
	ds_read_b128 v[8:11], v8
	s_waitcnt lgkmcnt(3)
	v_mfma_f32_32x32x16_bf16 v[64:79], v[12:15], v[132:135], v[64:79]
	v_add_u32_e32 v12, v230, v211
	ds_read_b128 v[12:15], v12
	ds_read_b128 v[16:19], v16
	s_waitcnt lgkmcnt(4)
	v_mfma_f32_32x32x16_bf16 v[64:79], v[20:23], v[128:131], v[64:79]
	s_waitcnt lgkmcnt(3)
	v_mfma_f32_32x32x16_bf16 v[48:63], v[4:7], v[0:3], 0
	v_add_u32_e32 v4, v230, v226
	v_add_u32_e32 v20, v230, v229
	s_waitcnt lgkmcnt(2)
	v_mfma_f32_32x32x16_bf16 v[48:63], v[8:11], v[152:155], v[48:63]
	v_add_u32_e32 v8, v230, v227
	ds_read_b128 v[4:7], v4
	ds_read_b128 v[8:11], v8
	s_waitcnt lgkmcnt(3)
	v_mfma_f32_32x32x16_bf16 v[48:63], v[12:15], v[148:151], v[48:63]
	v_add_u32_e32 v12, v230, v228
	ds_read_b128 v[12:15], v12
	ds_read_b128 v[20:23], v20
	s_waitcnt lgkmcnt(4)
	v_mfma_f32_32x32x16_bf16 v[48:63], v[16:19], v[144:147], v[48:63]
	s_waitcnt lgkmcnt(3)
	v_mfma_f32_32x32x16_bf16 v[48:63], v[4:7], v[140:143], v[48:63]
	v_add_u32_e32 v231, 0x14000, v173
	v_add_u32_e32 v4, v231, v209
	v_add_u32_e32 v16, v231, v218
	s_waitcnt lgkmcnt(2)
	v_mfma_f32_32x32x16_bf16 v[48:63], v[8:11], v[136:139], v[48:63]
	v_add_u32_e32 v8, v231, v210
	ds_read_b128 v[4:7], v4
	ds_read_b128 v[8:11], v8
	s_waitcnt lgkmcnt(3)
	v_mfma_f32_32x32x16_bf16 v[48:63], v[12:15], v[132:135], v[48:63]
	v_add_u32_e32 v12, v231, v211
	ds_read_b128 v[12:15], v12
	ds_read_b128 v[16:19], v16
	s_waitcnt lgkmcnt(4)
	v_mfma_f32_32x32x16_bf16 v[48:63], v[20:23], v[128:131], v[48:63]
	s_waitcnt lgkmcnt(3)
	v_mfma_f32_32x32x16_bf16 v[32:47], v[4:7], v[0:3], 0
	v_add_u32_e32 v4, v231, v226
	v_add_u32_e32 v20, v231, v229
	s_waitcnt lgkmcnt(2)
	v_mfma_f32_32x32x16_bf16 v[32:47], v[8:11], v[152:155], v[32:47]
	v_add_u32_e32 v8, v231, v227
	ds_read_b128 v[4:7], v4
	ds_read_b128 v[8:11], v8
	s_waitcnt lgkmcnt(3)
	v_mfma_f32_32x32x16_bf16 v[32:47], v[12:15], v[148:151], v[32:47]
	v_add_u32_e32 v12, v231, v228
	ds_read_b128 v[12:15], v12
	ds_read_b128 v[20:23], v20
	s_waitcnt lgkmcnt(4)
	v_mfma_f32_32x32x16_bf16 v[32:47], v[16:19], v[144:147], v[32:47]
	s_waitcnt lgkmcnt(3)
	v_mfma_f32_32x32x16_bf16 v[32:47], v[4:7], v[140:143], v[32:47]
	v_add_u32_e32 v232, 0x18000, v173
	v_add_u32_e32 v4, v232, v209
	v_add_u32_e32 v16, v232, v218
	s_waitcnt lgkmcnt(2)
	v_mfma_f32_32x32x16_bf16 v[32:47], v[8:11], v[136:139], v[32:47]
	v_add_u32_e32 v8, v232, v210
	ds_read_b128 v[4:7], v4
	ds_read_b128 v[8:11], v8
	s_waitcnt lgkmcnt(3)
	v_mfma_f32_32x32x16_bf16 v[32:47], v[12:15], v[132:135], v[32:47]
	v_add_u32_e32 v12, v232, v211
	ds_read_b128 v[12:15], v12
	ds_read_b128 v[156:159], v16
	s_waitcnt lgkmcnt(4)
	v_mfma_f32_32x32x16_bf16 v[32:47], v[20:23], v[128:131], v[32:47]
	s_waitcnt lgkmcnt(3)
	v_mfma_f32_32x32x16_bf16 v[16:31], v[4:7], v[0:3], 0
	v_add_u32_e32 v4, v232, v226
	v_add_u32_e32 v214, v232, v229
	s_waitcnt lgkmcnt(2)
	v_mfma_f32_32x32x16_bf16 v[16:31], v[8:11], v[152:155], v[16:31]
	v_add_u32_e32 v8, v232, v227
	ds_read_b128 v[4:7], v4
	ds_read_b128 v[8:11], v8
	s_waitcnt lgkmcnt(3)
	v_mfma_f32_32x32x16_bf16 v[16:31], v[12:15], v[148:151], v[16:31]
	v_add_u32_e32 v12, v232, v228
	ds_read_b128 v[12:15], v12
	ds_read_b128 v[214:217], v214
	s_waitcnt lgkmcnt(4)
	v_mfma_f32_32x32x16_bf16 v[16:31], v[156:159], v[144:147], v[16:31]
	s_waitcnt lgkmcnt(3)
	v_mfma_f32_32x32x16_bf16 v[16:31], v[4:7], v[140:143], v[16:31]
	v_add_u32_e32 v233, 0x1c000, v173
	v_add_u32_e32 v4, v233, v209
	s_waitcnt lgkmcnt(2)
; #define LAS __attribute__((address_space(3)))
; DI void attn_prompt_item(const Params& p, int item, ldsp lds, int tid_) {
;     ...
;   for (int sh = 0; sh < 2; ++sh) {
;     if (sh == 1) {
;       __builtin_amdgcn_sched_barrier(0);
; #pragma unroll
;       for (int s = 0; s < 8; ++s) qreg[s] = *(const bf16x8*)(qx + qrow * D + h * 256 + 16 * (8 + s) + 8 * h2);
;     }
;     {
;       bf16x8 kfa[4], kfb[4];
;     ...
; #pragma unroll
;       for (int j = 0; j < 4; ++j) kfa[j] = *(const LAS bf16x8*)KF_ADDR(0, j);
; #pragma unroll
;       for (int gi = 0; gi < 16; ++gi) {
;         if (gi + 1 < 16) {
; #pragma unroll
;           for (int j = 0; j < 4; ++j) { if (gi & 1) kfa[j] = *(const LAS bf16x8*)KF_ADDR(gi + 1, j); else kfb[j] = *(const LAS bf16x8*)KF_ADDR(gi + 1, j); } }
; #pragma unroll
;         for (int j = 0; j < 4; ++j) S[gi >> 1] = __builtin_amdgcn_mfma_f32_32x32x16_bf16((gi & 1) ? kfb[j] : kfa[j], qreg[(gi & 1) * 4 + j], S[gi >> 1], 0, 0, 0);
;         __builtin_amdgcn_sched_barrier(0);
;       }
	v_mfma_f32_32x32x16_bf16 v[16:31], v[8:11], v[136:139], v[16:31]
	v_add_u32_e32 v8, v233, v210
	ds_read_b128 v[4:7], v4
	ds_read_b128 v[156:159], v8
	v_add_u32_e32 v8, v233, v211
	v_add_u32_e32 v9, v233, v218
	ds_read_b128 v[218:221], v8
	ds_read_b128 v[222:225], v9
	s_waitcnt lgkmcnt(5)
	v_mfma_f32_32x32x16_bf16 v[16:31], v[12:15], v[132:135], v[16:31]
	s_waitcnt lgkmcnt(4)
	v_mfma_f32_32x32x16_bf16 v[16:31], v[214:217], v[128:131], v[16:31]
	s_waitcnt lgkmcnt(3)
	v_mfma_f32_32x32x16_bf16 v[0:15], v[4:7], v[0:3], 0
	v_add_u32_e32 v209, v233, v229
	s_waitcnt lgkmcnt(2)
	v_mfma_f32_32x32x16_bf16 v[0:15], v[156:159], v[152:155], v[0:15]
	v_add_u32_e32 v152, v233, v226
	v_add_u32_e32 v153, v233, v227
	v_add_u32_e32 v156, v233, v228
	s_waitcnt lgkmcnt(1)
	v_mfma_f32_32x32x16_bf16 v[0:15], v[218:221], v[148:151], v[0:15]
	ds_read_b128 v[148:151], v152
	ds_read_b128 v[152:155], v153
	ds_read_b128 v[156:159], v156
	ds_read_b128 v[214:217], v209
	s_waitcnt lgkmcnt(4)
	v_mfma_f32_32x32x16_bf16 v[0:15], v[222:225], v[144:147], v[0:15]
	s_waitcnt lgkmcnt(3)
	v_mfma_f32_32x32x16_bf16 v[0:15], v[148:151], v[140:143], v[0:15]
	s_waitcnt lgkmcnt(2)
	v_mfma_f32_32x32x16_bf16 v[0:15], v[152:155], v[136:139], v[0:15]
	s_waitcnt lgkmcnt(1)
	v_mfma_f32_32x32x16_bf16 v[0:15], v[156:159], v[132:135], v[0:15]
	s_waitcnt lgkmcnt(0)
	v_mfma_f32_32x32x16_bf16 v[0:15], v[214:217], v[128:131], v[0:15]
	global_load_dwordx4 v[156:159], v[166:167], off offset:256
	global_load_dwordx4 v[152:155], v[166:167], off offset:288
	global_load_dwordx4 v[148:151], v[166:167], off offset:320
	global_load_dwordx4 v[144:147], v[166:167], off offset:352
	global_load_dwordx4 v[140:143], v[166:167], off offset:384
	global_load_dwordx4 v[136:139], v[166:167], off offset:416
	global_load_dwordx4 v[132:135], v[166:167], off offset:448
	global_load_dwordx4 v[128:131], v[166:167], off offset:480
	v_bitop3_b32 v166, v208, v175, 16 bitop3:0x36
	v_lshlrev_b32_e32 v166, 4, v166
	v_add_u32_e32 v167, v173, v166
	ds_read_b128 v[214:217], v167
	v_bitop3_b32 v209, v208, v175, 18 bitop3:0x36
	v_lshlrev_b32_e32 v234, 4, v209
	v_add_u32_e32 v235, v173, v234
	ds_read_b128 v[218:221], v235
	v_bitop3_b32 v209, v208, v175, 20 bitop3:0x36
	v_lshlrev_b32_e32 v236, 4, v209
	v_bitop3_b32 v209, v208, v175, 22 bitop3:0x36
	v_add_u32_e32 v237, v173, v236
	v_lshlrev_b32_e32 v238, 4, v209
	v_add_u32_e32 v239, v173, v238
	v_bitop3_b32 v209, v208, v175, 24 bitop3:0x36
	v_lshlrev_b32_e32 v240, 4, v209
	v_bitop3_b32 v209, v208, v175, 26 bitop3:0x36
	v_lshlrev_b32_e32 v242, 4, v209
	v_bitop3_b32 v209, v208, v175, 28 bitop3:0x36
	v_lshlrev_b32_e32 v244, 4, v209
	v_bitop3_b32 v208, v208, v175, 30 bitop3:0x36
	v_add_u32_e32 v241, v173, v240
	v_add_u32_e32 v245, v173, v244
	v_lshlrev_b32_e32 v246, 4, v208
	v_add_u32_e32 v243, v173, v242
	v_add_u32_e32 v247, v173, v246
	s_waitcnt vmcnt(7) lgkmcnt(1)
	v_mfma_f32_32x32x16_bf16 v[112:127], v[214:217], v[156:159], v[112:127]
	ds_read_b128 v[214:217], v237
	ds_read_b128 v[222:225], v239
	s_waitcnt vmcnt(6) lgkmcnt(2)
	v_mfma_f32_32x32x16_bf16 v[112:127], v[218:221], v[152:155], v[112:127]
	ds_read_b128 v[218:221], v241
	ds_read_b128 v[226:229], v243
	s_waitcnt vmcnt(5) lgkmcnt(3)
	v_mfma_f32_32x32x16_bf16 v[112:127], v[214:217], v[148:151], v[112:127]
	ds_read_b128 v[208:211], v245
	ds_read_b128 v[214:217], v247
	s_waitcnt vmcnt(4) lgkmcnt(4)
	v_mfma_f32_32x32x16_bf16 v[112:127], v[222:225], v[144:147], v[112:127]
	s_waitcnt vmcnt(3) lgkmcnt(3)
	v_mfma_f32_32x32x16_bf16 v[112:127], v[218:221], v[140:143], v[112:127]
	s_waitcnt vmcnt(2) lgkmcnt(2)
	v_mfma_f32_32x32x16_bf16 v[112:127], v[226:229], v[136:139], v[112:127]
	s_waitcnt vmcnt(1) lgkmcnt(1)
	v_mfma_f32_32x32x16_bf16 v[112:127], v[208:211], v[132:135], v[112:127]
	ds_read_b128 v[208:211], v167 offset:16384
	ds_read_b128 v[218:221], v235 offset:16384
	ds_read_b128 v[222:225], v237 offset:16384
	ds_read_b128 v[226:229], v239 offset:16384
	s_waitcnt vmcnt(0) lgkmcnt(4)
	v_mfma_f32_32x32x16_bf16 v[112:127], v[214:217], v[128:131], v[112:127]
	s_waitcnt lgkmcnt(3)
	v_mfma_f32_32x32x16_bf16 v[96:111], v[208:211], v[156:159], v[96:111]
	s_waitcnt lgkmcnt(2)
	v_mfma_f32_32x32x16_bf16 v[96:111], v[218:221], v[152:155], v[96:111]
	s_waitcnt lgkmcnt(1)
	v_mfma_f32_32x32x16_bf16 v[96:111], v[222:225], v[148:151], v[96:111]
	ds_read_b128 v[208:211], v241 offset:16384
	ds_read_b128 v[214:217], v243 offset:16384
	ds_read_b128 v[218:221], v245 offset:16384
	ds_read_b128 v[222:225], v247 offset:16384
	s_waitcnt lgkmcnt(4)
	v_mfma_f32_32x32x16_bf16 v[96:111], v[226:229], v[144:147], v[96:111]
	s_waitcnt lgkmcnt(3)
	v_mfma_f32_32x32x16_bf16 v[96:111], v[208:211], v[140:143], v[96:111]
	s_waitcnt lgkmcnt(2)
	v_mfma_f32_32x32x16_bf16 v[96:111], v[214:217], v[136:139], v[96:111]
	s_waitcnt lgkmcnt(1)
	v_mfma_f32_32x32x16_bf16 v[96:111], v[218:221], v[132:135], v[96:111]
	ds_read_b128 v[208:211], v167 offset:32768
	ds_read_b128 v[214:217], v235 offset:32768
	ds_read_b128 v[218:221], v237 offset:32768
	ds_read_b128 v[226:229], v239 offset:32768
	s_waitcnt lgkmcnt(4)
	v_mfma_f32_32x32x16_bf16 v[96:111], v[222:225], v[128:131], v[96:111]
	s_waitcnt lgkmcnt(3)
	v_mfma_f32_32x32x16_bf16 v[80:95], v[208:211], v[156:159], v[80:95]
	s_waitcnt lgkmcnt(2)
	v_mfma_f32_32x32x16_bf16 v[80:95], v[214:217], v[152:155], v[80:95]
	s_waitcnt lgkmcnt(1)
	v_mfma_f32_32x32x16_bf16 v[80:95], v[218:221], v[148:151], v[80:95]
	ds_read_b128 v[208:211], v241 offset:32768
	ds_read_b128 v[214:217], v243 offset:32768
	ds_read_b128 v[218:221], v245 offset:32768
	ds_read_b128 v[222:225], v247 offset:32768
	s_waitcnt lgkmcnt(4)
; #define LAS __attribute__((address_space(3)))
; DI void attn_prompt_item(const Params& p, int item, ldsp lds, int tid_) {
;     ...
;     {
;       bf16x8 kfa[4], kfb[4];
;     ...
; #pragma unroll
;       for (int j = 0; j < 4; ++j) kfa[j] = *(const LAS bf16x8*)KF_ADDR(0, j);
; #pragma unroll
;       for (int gi = 0; gi < 16; ++gi) {
;         if (gi + 1 < 16) {
; #pragma unroll
;           for (int j = 0; j < 4; ++j) { if (gi & 1) kfa[j] = *(const LAS bf16x8*)KF_ADDR(gi + 1, j); else kfb[j] = *(const LAS bf16x8*)KF_ADDR(gi + 1, j); } }
; #pragma unroll
;         for (int j = 0; j < 4; ++j) S[gi >> 1] = __builtin_amdgcn_mfma_f32_32x32x16_bf16((gi & 1) ? kfb[j] : kfa[j], qreg[(gi & 1) * 4 + j], S[gi >> 1], 0, 0, 0);
;         __builtin_amdgcn_sched_barrier(0);
;       }
	v_mfma_f32_32x32x16_bf16 v[80:95], v[226:229], v[144:147], v[80:95]
	s_waitcnt lgkmcnt(3)
	v_mfma_f32_32x32x16_bf16 v[80:95], v[208:211], v[140:143], v[80:95]
	s_waitcnt lgkmcnt(2)
	v_mfma_f32_32x32x16_bf16 v[80:95], v[214:217], v[136:139], v[80:95]
	s_waitcnt lgkmcnt(1)
	v_mfma_f32_32x32x16_bf16 v[80:95], v[218:221], v[132:135], v[80:95]
	ds_read_b128 v[208:211], v167 offset:49152
	ds_read_b128 v[214:217], v235 offset:49152
	ds_read_b128 v[218:221], v237 offset:49152
	ds_read_b128 v[226:229], v239 offset:49152
	s_waitcnt lgkmcnt(4)
	v_mfma_f32_32x32x16_bf16 v[80:95], v[222:225], v[128:131], v[80:95]
	s_waitcnt lgkmcnt(3)
	v_mfma_f32_32x32x16_bf16 v[64:79], v[208:211], v[156:159], v[64:79]
	s_waitcnt lgkmcnt(2)
	v_mfma_f32_32x32x16_bf16 v[64:79], v[214:217], v[152:155], v[64:79]
	s_waitcnt lgkmcnt(1)
	v_mfma_f32_32x32x16_bf16 v[64:79], v[218:221], v[148:151], v[64:79]
	ds_read_b128 v[208:211], v241 offset:49152
	ds_read_b128 v[214:217], v243 offset:49152
	ds_read_b128 v[218:221], v245 offset:49152
	ds_read_b128 v[222:225], v247 offset:49152
	s_waitcnt lgkmcnt(4)
	v_mfma_f32_32x32x16_bf16 v[64:79], v[226:229], v[144:147], v[64:79]
	s_waitcnt lgkmcnt(3)
	v_mfma_f32_32x32x16_bf16 v[64:79], v[208:211], v[140:143], v[64:79]
	v_add_u32_e32 v167, v230, v166
	v_add_u32_e32 v226, v230, v238
	s_waitcnt lgkmcnt(2)
	v_mfma_f32_32x32x16_bf16 v[64:79], v[214:217], v[136:139], v[64:79]
	v_add_u32_e32 v214, v230, v234
	ds_read_b128 v[208:211], v167
	ds_read_b128 v[214:217], v214
	v_add_u32_e32 v167, v230, v236
	s_waitcnt lgkmcnt(3)
	v_mfma_f32_32x32x16_bf16 v[64:79], v[218:221], v[132:135], v[64:79]
	ds_read_b128 v[218:221], v167
	ds_read_b128 v[226:229], v226
	s_waitcnt lgkmcnt(4)
	v_mfma_f32_32x32x16_bf16 v[64:79], v[222:225], v[128:131], v[64:79]
	s_waitcnt lgkmcnt(3)
	v_mfma_f32_32x32x16_bf16 v[48:63], v[208:211], v[156:159], v[48:63]
	v_add_u32_e32 v167, v230, v240
	v_add_u32_e32 v222, v230, v246
	s_waitcnt lgkmcnt(2)
	v_mfma_f32_32x32x16_bf16 v[48:63], v[214:217], v[152:155], v[48:63]
	v_add_u32_e32 v214, v230, v242
	ds_read_b128 v[208:211], v167
	ds_read_b128 v[214:217], v214
	v_add_u32_e32 v167, v230, v244
	s_waitcnt lgkmcnt(3)
	v_mfma_f32_32x32x16_bf16 v[48:63], v[218:221], v[148:151], v[48:63]
	ds_read_b128 v[218:221], v167
	ds_read_b128 v[222:225], v222
	s_waitcnt lgkmcnt(4)
	v_mfma_f32_32x32x16_bf16 v[48:63], v[226:229], v[144:147], v[48:63]
	s_waitcnt lgkmcnt(3)
	v_mfma_f32_32x32x16_bf16 v[48:63], v[208:211], v[140:143], v[48:63]
	v_add_u32_e32 v167, v231, v166
	v_add_u32_e32 v226, v231, v238
	s_waitcnt lgkmcnt(2)
	v_mfma_f32_32x32x16_bf16 v[48:63], v[214:217], v[136:139], v[48:63]
	v_add_u32_e32 v214, v231, v234
	ds_read_b128 v[208:211], v167
	ds_read_b128 v[214:217], v214
	v_add_u32_e32 v167, v231, v236
	s_waitcnt lgkmcnt(3)
	v_mfma_f32_32x32x16_bf16 v[48:63], v[218:221], v[132:135], v[48:63]
	ds_read_b128 v[218:221], v167
	ds_read_b128 v[226:229], v226
	s_waitcnt lgkmcnt(4)
	v_mfma_f32_32x32x16_bf16 v[48:63], v[222:225], v[128:131], v[48:63]
	s_waitcnt lgkmcnt(3)
	v_mfma_f32_32x32x16_bf16 v[32:47], v[208:211], v[156:159], v[32:47]
	v_add_u32_e32 v167, v231, v240
	v_add_u32_e32 v222, v231, v246
	s_waitcnt lgkmcnt(2)
	v_mfma_f32_32x32x16_bf16 v[32:47], v[214:217], v[152:155], v[32:47]
	v_add_u32_e32 v214, v231, v242
	ds_read_b128 v[208:211], v167
	ds_read_b128 v[214:217], v214
	v_add_u32_e32 v167, v231, v244
	s_waitcnt lgkmcnt(3)
	v_mfma_f32_32x32x16_bf16 v[32:47], v[218:221], v[148:151], v[32:47]
	ds_read_b128 v[218:221], v167
	ds_read_b128 v[222:225], v222
	s_waitcnt lgkmcnt(4)
	v_mfma_f32_32x32x16_bf16 v[32:47], v[226:229], v[144:147], v[32:47]
	s_waitcnt lgkmcnt(3)
	v_mfma_f32_32x32x16_bf16 v[32:47], v[208:211], v[140:143], v[32:47]
	v_add_u32_e32 v167, v232, v166
	v_add_u32_e32 v226, v232, v238
	s_waitcnt lgkmcnt(2)
	v_mfma_f32_32x32x16_bf16 v[32:47], v[214:217], v[136:139], v[32:47]
	v_add_u32_e32 v214, v232, v234
	ds_read_b128 v[208:211], v167
	ds_read_b128 v[214:217], v214
	v_add_u32_e32 v167, v232, v236
	s_waitcnt lgkmcnt(3)
	v_mfma_f32_32x32x16_bf16 v[32:47], v[218:221], v[132:135], v[32:47]
	ds_read_b128 v[218:221], v167
	ds_read_b128 v[226:229], v226
	s_waitcnt lgkmcnt(4)
	v_mfma_f32_32x32x16_bf16 v[32:47], v[222:225], v[128:131], v[32:47]
	s_waitcnt lgkmcnt(3)
	v_mfma_f32_32x32x16_bf16 v[16:31], v[208:211], v[156:159], v[16:31]
	v_add_u32_e32 v167, v232, v240
	v_add_u32_e32 v222, v232, v246
	s_waitcnt lgkmcnt(2)
	v_mfma_f32_32x32x16_bf16 v[16:31], v[214:217], v[152:155], v[16:31]
	v_add_u32_e32 v214, v232, v242
	ds_read_b128 v[208:211], v167
	ds_read_b128 v[214:217], v214
	v_add_u32_e32 v167, v232, v244
	s_waitcnt lgkmcnt(3)
	v_mfma_f32_32x32x16_bf16 v[16:31], v[218:221], v[148:151], v[16:31]
	ds_read_b128 v[218:221], v167
	ds_read_b128 v[222:225], v222
	s_waitcnt lgkmcnt(4)
	v_mfma_f32_32x32x16_bf16 v[16:31], v[226:229], v[144:147], v[16:31]
	s_waitcnt lgkmcnt(3)
	v_mfma_f32_32x32x16_bf16 v[16:31], v[208:211], v[140:143], v[16:31]
	v_add_u32_e32 v166, v233, v166
	v_add_u32_e32 v167, v233, v234
	s_waitcnt lgkmcnt(2)
	v_mfma_f32_32x32x16_bf16 v[16:31], v[214:217], v[136:139], v[16:31]
	ds_read_b128 v[208:211], v166
	ds_read_b128 v[214:217], v167
	v_add_u32_e32 v166, v233, v236
	v_add_u32_e32 v167, v233, v238
	s_waitcnt lgkmcnt(3)
	v_mfma_f32_32x32x16_bf16 v[16:31], v[218:221], v[132:135], v[16:31]
	ds_read_b128 v[218:221], v166
	ds_read_b128 v[226:229], v167
	s_waitcnt lgkmcnt(4)
	v_mfma_f32_32x32x16_bf16 v[16:31], v[222:225], v[128:131], v[16:31]
	s_waitcnt lgkmcnt(3)
	v_mfma_f32_32x32x16_bf16 v[0:15], v[208:211], v[156:159], v[0:15]
	v_add_u32_e32 v156, v233, v244
	v_add_u32_e32 v166, v233, v246
	s_waitcnt lgkmcnt(2)
; DI void attn_prompt_item(const Params& p, int item, ldsp lds, int tid_) {
;     ...
;         for (int j = 0; j < 4; ++j) S[gi >> 1] = __builtin_amdgcn_mfma_f32_32x32x16_bf16((gi & 1) ? kfb[j] : kfa[j], qreg[(gi & 1) * 4 + j], S[gi >> 1], 0, 0, 0);
;         __builtin_amdgcn_sched_barrier(0);
;       }
;     ...
;     }
;   }
;   float mx = -1e30f;
; #pragma unroll
;   for (int kt = 0; kt < 8; ++kt)
; #pragma unroll
;     for (int i = 0; i < 16; ++i) mx = fmaxf(mx, S[kt][i]);
;   mx = fmaxf(mx, __shfl_xor(mx, 32));
;   float sum = 0.f;
; #pragma unroll
;   for (int kt = 0; kt < 8; ++kt)
; #pragma unroll
;     for (int i = 0; i < 16; ++i) { const float e = __expf(S[kt][i] - mx); S[kt][i] = e; sum += e; }
;   sum += __shfl_xor(sum, 32);
;   const float inv = 1.f / sum;
	v_mfma_f32_32x32x16_bf16 v[0:15], v[214:217], v[152:155], v[0:15]
	v_add_u32_e32 v152, v233, v240
	v_add_u32_e32 v153, v233, v242
	s_waitcnt lgkmcnt(1)
	v_mfma_f32_32x32x16_bf16 v[0:15], v[218:221], v[148:151], v[0:15]
	ds_read_b128 v[148:151], v152
	ds_read_b128 v[152:155], v153
	ds_read_b128 v[156:159], v156
	ds_read_b128 v[208:211], v166
	s_waitcnt lgkmcnt(4)
	v_mfma_f32_32x32x16_bf16 v[0:15], v[226:229], v[144:147], v[0:15]
	s_waitcnt lgkmcnt(3)
	v_mfma_f32_32x32x16_bf16 v[0:15], v[148:151], v[140:143], v[0:15]
	s_waitcnt lgkmcnt(2)
	v_mfma_f32_32x32x16_bf16 v[0:15], v[152:155], v[136:139], v[0:15]
	s_waitcnt lgkmcnt(1)
	v_mfma_f32_32x32x16_bf16 v[0:15], v[156:159], v[132:135], v[0:15]
	s_waitcnt lgkmcnt(0)
	v_mfma_f32_32x32x16_bf16 v[0:15], v[208:211], v[128:131], v[0:15]
	v_max3_f32 v128, v112, s35, v113
	v_max3_f32 v128, v128, v114, v115
	v_max3_f32 v128, v128, v116, v117
	v_max3_f32 v128, v128, v118, v119
	v_max3_f32 v128, v128, v120, v121
	v_max3_f32 v128, v128, v122, v123
	v_max3_f32 v128, v128, v124, v125
	v_max3_f32 v128, v128, v126, v127
	v_max3_f32 v128, v128, v96, v97
	v_max3_f32 v128, v128, v98, v99
	v_max3_f32 v128, v128, v100, v101
	v_max3_f32 v128, v128, v102, v103
	v_max3_f32 v128, v128, v104, v105
	v_max3_f32 v128, v128, v106, v107
	v_max3_f32 v128, v128, v108, v109
	v_max3_f32 v128, v128, v110, v111
	v_max3_f32 v128, v128, v80, v81
	v_max3_f32 v128, v128, v82, v83
	v_max3_f32 v128, v128, v84, v85
	v_max3_f32 v128, v128, v86, v87
	v_max3_f32 v128, v128, v88, v89
	v_max3_f32 v128, v128, v90, v91
	v_max3_f32 v128, v128, v92, v93
	v_max3_f32 v128, v128, v94, v95
	v_max3_f32 v128, v128, v64, v65
	v_max3_f32 v128, v128, v66, v67
	v_max3_f32 v128, v128, v68, v69
	v_max3_f32 v128, v128, v70, v71
	v_max3_f32 v128, v128, v72, v73
	v_max3_f32 v128, v128, v74, v75
	v_max3_f32 v128, v128, v76, v77
	v_max3_f32 v128, v128, v78, v79
	v_max3_f32 v128, v128, v48, v49
	v_max3_f32 v128, v128, v50, v51
	v_max3_f32 v128, v128, v52, v53
	v_max3_f32 v128, v128, v54, v55
	v_max3_f32 v128, v128, v56, v57
	v_max3_f32 v128, v128, v58, v59
	v_max3_f32 v128, v128, v60, v61
	v_max3_f32 v128, v128, v62, v63
	v_max3_f32 v128, v128, v32, v33
	v_max3_f32 v128, v128, v34, v35
	v_max3_f32 v128, v128, v36, v37
	v_max3_f32 v128, v128, v38, v39
	v_max3_f32 v128, v128, v40, v41
	v_max3_f32 v128, v128, v42, v43
	v_max3_f32 v128, v128, v44, v45
	v_max3_f32 v128, v128, v46, v47
	v_max3_f32 v128, v128, v16, v17
	v_max3_f32 v128, v128, v18, v19
	v_max3_f32 v128, v128, v20, v21
	v_max3_f32 v128, v128, v22, v23
	v_max3_f32 v128, v128, v24, v25
	v_max3_f32 v128, v128, v26, v27
	v_max3_f32 v128, v128, v28, v29
	v_max3_f32 v128, v128, v30, v31
	v_max3_f32 v128, v128, v0, v1
	v_max3_f32 v128, v128, v2, v3
	v_max3_f32 v128, v128, v4, v5
	v_max3_f32 v128, v128, v6, v7
	v_max3_f32 v128, v128, v8, v9
	v_max3_f32 v128, v128, v10, v11
	v_cmp_lt_i32_e32 vcc, v169, v170
	v_max3_f32 v128, v128, v12, v13
	v_max3_f32 v128, v128, v14, v15
	v_cndmask_b32_e32 v129, v168, v169, vcc
	v_lshlrev_b32_e32 v132, 2, v129
	ds_bpermute_b32 v129, v132, v128
	s_lshl_b32 s28, s28, 10
	s_or_b32 s3, s3, s28
	s_waitcnt lgkmcnt(0)
	s_barrier
	v_max_f32_e32 v129, v129, v129
	v_max_f32_e32 v134, v128, v129
	v_sub_f32_e32 v112, v112, v134
	v_sub_f32_e32 v113, v113, v134
	v_mul_f32_e32 v112, 0x3fb8aa3b, v112
	v_exp_f32_e32 v133, v112
	v_mul_f32_e32 v112, 0x3fb8aa3b, v113
	v_exp_f32_e32 v135, v112
	v_sub_f32_e32 v112, v114, v134
	v_mul_f32_e32 v112, 0x3fb8aa3b, v112
	v_exp_f32_e32 v136, v112
	v_sub_f32_e32 v112, v115, v134
	v_mul_f32_e32 v112, 0x3fb8aa3b, v112
	v_exp_f32_e32 v137, v112
	v_add_f32_e32 v112, 0, v133
	v_add_f32_e32 v112, v135, v112
	v_add_f32_e32 v112, v136, v112
	v_add_f32_e32 v114, v137, v112
	v_sub_f32_e32 v112, v116, v134
	v_mul_f32_e32 v112, 0x3fb8aa3b, v112
	v_exp_f32_e32 v138, v112
	v_sub_f32_e32 v112, v117, v134
	v_mul_f32_e32 v112, 0x3fb8aa3b, v112
	v_exp_f32_e32 v139, v112
	v_sub_f32_e32 v112, v118, v134
	v_mul_f32_e32 v112, 0x3fb8aa3b, v112
	v_sub_f32_e32 v113, v119, v134
	v_exp_f32_e32 v112, v112
	v_mul_f32_e32 v113, 0x3fb8aa3b, v113
	v_exp_f32_e32 v113, v113
	v_add_f32_e32 v114, v138, v114
	v_add_f32_e32 v114, v139, v114
	v_add_f32_e32 v114, v112, v114
	v_add_f32_e32 v118, v113, v114
	v_sub_f32_e32 v114, v120, v134
	v_mul_f32_e32 v114, 0x3fb8aa3b, v114
	v_sub_f32_e32 v115, v121, v134
	v_exp_f32_e32 v114, v114
	v_mul_f32_e32 v115, 0x3fb8aa3b, v115
	v_sub_f32_e32 v116, v122, v134
	v_exp_f32_e32 v115, v115
	v_mul_f32_e32 v116, 0x3fb8aa3b, v116
	v_sub_f32_e32 v117, v123, v134
	v_exp_f32_e32 v116, v116
	v_mul_f32_e32 v117, 0x3fb8aa3b, v117
	v_exp_f32_e32 v117, v117
	v_add_f32_e32 v118, v114, v118
	v_add_f32_e32 v118, v115, v118
	v_add_f32_e32 v118, v116, v118
	v_add_f32_e32 v122, v117, v118
	v_sub_f32_e32 v118, v124, v134
	v_mul_f32_e32 v118, 0x3fb8aa3b, v118
	v_sub_f32_e32 v119, v125, v134
	v_exp_f32_e32 v118, v118
	v_mul_f32_e32 v119, 0x3fb8aa3b, v119
	v_sub_f32_e32 v120, v126, v134
	v_exp_f32_e32 v119, v119
	v_mul_f32_e32 v120, 0x3fb8aa3b, v120
	v_sub_f32_e32 v121, v127, v134
	v_exp_f32_e32 v120, v120
	v_mul_f32_e32 v121, 0x3fb8aa3b, v121
	v_sub_f32_e32 v96, v96, v134
	v_exp_f32_e32 v121, v121
	v_mul_f32_e32 v96, 0x3fb8aa3b, v96
	v_sub_f32_e32 v97, v97, v134
	v_add_f32_e32 v122, v118, v122
	v_exp_f32_e32 v96, v96
	v_mul_f32_e32 v97, 0x3fb8aa3b, v97
	v_sub_f32_e32 v98, v98, v134
	v_add_f32_e32 v122, v119, v122
	v_exp_f32_e32 v97, v97
	v_mul_f32_e32 v98, 0x3fb8aa3b, v98
	v_sub_f32_e32 v99, v99, v134
	v_add_f32_e32 v122, v120, v122
	v_exp_f32_e32 v98, v98
	v_mul_f32_e32 v99, 0x3fb8aa3b, v99
	v_sub_f32_e32 v100, v100, v134
	v_add_f32_e32 v122, v121, v122
	v_exp_f32_e32 v99, v99
; DI void attn_prompt_item(const Params& p, int item, ldsp lds, int tid_) {
;     ...
;   float sum = 0.f;
; #pragma unroll
;   for (int kt = 0; kt < 8; ++kt)
; #pragma unroll
;     for (int i = 0; i < 16; ++i) { const float e = __expf(S[kt][i] - mx); S[kt][i] = e; sum += e; }
	v_mul_f32_e32 v100, 0x3fb8aa3b, v100
	v_sub_f32_e32 v101, v101, v134
	v_add_f32_e32 v122, v96, v122
	v_exp_f32_e32 v100, v100
	v_mul_f32_e32 v101, 0x3fb8aa3b, v101
	v_sub_f32_e32 v102, v102, v134
	v_add_f32_e32 v122, v97, v122
	v_exp_f32_e32 v101, v101
	v_mul_f32_e32 v102, 0x3fb8aa3b, v102
	v_sub_f32_e32 v103, v103, v134
	v_add_f32_e32 v122, v98, v122
	v_exp_f32_e32 v102, v102
	v_mul_f32_e32 v103, 0x3fb8aa3b, v103
	v_sub_f32_e32 v104, v104, v134
	v_add_f32_e32 v122, v99, v122
	v_exp_f32_e32 v103, v103
	v_mul_f32_e32 v104, 0x3fb8aa3b, v104
	v_sub_f32_e32 v105, v105, v134
	v_sub_f32_e32 v108, v108, v134
	v_add_f32_e32 v122, v100, v122
	v_exp_f32_e32 v104, v104
	v_mul_f32_e32 v105, 0x3fb8aa3b, v105
	v_sub_f32_e32 v106, v106, v134
	v_mul_f32_e32 v108, 0x3fb8aa3b, v108
	v_add_f32_e32 v122, v101, v122
	v_exp_f32_e32 v105, v105
	v_mul_f32_e32 v106, 0x3fb8aa3b, v106
	v_sub_f32_e32 v107, v107, v134
	v_exp_f32_e32 v128, v108
	v_sub_f32_e32 v108, v109, v134
	v_add_f32_e32 v122, v102, v122
	v_exp_f32_e32 v106, v106
	v_mul_f32_e32 v107, 0x3fb8aa3b, v107
	v_mul_f32_e32 v108, 0x3fb8aa3b, v108
	v_add_f32_e32 v122, v103, v122
	v_exp_f32_e32 v107, v107
	v_exp_f32_e32 v129, v108
	v_sub_f32_e32 v108, v110, v134
	v_add_f32_e32 v122, v104, v122
	v_mul_f32_e32 v108, 0x3fb8aa3b, v108
	v_add_f32_e32 v122, v105, v122
	v_exp_f32_e32 v130, v108
	v_sub_f32_e32 v108, v111, v134
	v_add_f32_e32 v122, v106, v122
	v_mul_f32_e32 v108, 0x3fb8aa3b, v108
	v_sub_f32_e32 v80, v80, v134
	v_add_f32_e32 v122, v107, v122
	v_exp_f32_e32 v131, v108
	v_mul_f32_e32 v80, 0x3fb8aa3b, v80
	v_sub_f32_e32 v81, v81, v134
	v_add_f32_e32 v108, v128, v122
	v_exp_f32_e32 v80, v80
	v_mul_f32_e32 v81, 0x3fb8aa3b, v81
	v_sub_f32_e32 v82, v82, v134
	v_add_f32_e32 v108, v129, v108
	v_exp_f32_e32 v81, v81
	v_mul_f32_e32 v82, 0x3fb8aa3b, v82
	v_sub_f32_e32 v83, v83, v134
	v_add_f32_e32 v108, v130, v108
	v_exp_f32_e32 v82, v82
	v_mul_f32_e32 v83, 0x3fb8aa3b, v83
	v_sub_f32_e32 v84, v84, v134
	v_add_f32_e32 v108, v131, v108
	v_exp_f32_e32 v83, v83
	v_mul_f32_e32 v84, 0x3fb8aa3b, v84
	v_sub_f32_e32 v85, v85, v134
	v_add_f32_e32 v108, v80, v108
	v_exp_f32_e32 v84, v84
	v_mul_f32_e32 v85, 0x3fb8aa3b, v85
	v_sub_f32_e32 v86, v86, v134
	v_add_f32_e32 v108, v81, v108
	v_exp_f32_e32 v85, v85
	v_mul_f32_e32 v86, 0x3fb8aa3b, v86
	v_sub_f32_e32 v87, v87, v134
	v_add_f32_e32 v108, v82, v108
	v_exp_f32_e32 v86, v86
	v_mul_f32_e32 v87, 0x3fb8aa3b, v87
	v_sub_f32_e32 v88, v88, v134
	v_add_f32_e32 v108, v83, v108
	v_exp_f32_e32 v87, v87
	v_mul_f32_e32 v88, 0x3fb8aa3b, v88
	v_sub_f32_e32 v89, v89, v134
	v_add_f32_e32 v108, v84, v108
	v_exp_f32_e32 v88, v88
	v_mul_f32_e32 v89, 0x3fb8aa3b, v89
	v_sub_f32_e32 v90, v90, v134
	v_add_f32_e32 v108, v85, v108
	v_exp_f32_e32 v89, v89
	v_mul_f32_e32 v90, 0x3fb8aa3b, v90
	v_sub_f32_e32 v91, v91, v134
	v_add_f32_e32 v108, v86, v108
	v_exp_f32_e32 v90, v90
	v_mul_f32_e32 v91, 0x3fb8aa3b, v91
	v_sub_f32_e32 v92, v92, v134
	v_add_f32_e32 v108, v87, v108
	v_exp_f32_e32 v91, v91
	v_mul_f32_e32 v92, 0x3fb8aa3b, v92
	v_sub_f32_e32 v93, v93, v134
	v_add_f32_e32 v108, v88, v108
	v_exp_f32_e32 v92, v92
	v_mul_f32_e32 v93, 0x3fb8aa3b, v93
	v_sub_f32_e32 v94, v94, v134
	v_add_f32_e32 v108, v89, v108
	v_exp_f32_e32 v93, v93
	v_mul_f32_e32 v94, 0x3fb8aa3b, v94
	v_sub_f32_e32 v95, v95, v134
	v_add_f32_e32 v108, v90, v108
	v_exp_f32_e32 v94, v94
	v_mul_f32_e32 v95, 0x3fb8aa3b, v95
	v_sub_f32_e32 v64, v64, v134
	v_add_f32_e32 v108, v91, v108
	v_exp_f32_e32 v95, v95
	v_mul_f32_e32 v64, 0x3fb8aa3b, v64
	v_sub_f32_e32 v65, v65, v134
	v_add_f32_e32 v108, v92, v108
	v_exp_f32_e32 v64, v64
	v_mul_f32_e32 v65, 0x3fb8aa3b, v65
	v_sub_f32_e32 v66, v66, v134
	v_add_f32_e32 v108, v93, v108
	v_exp_f32_e32 v65, v65
	v_mul_f32_e32 v66, 0x3fb8aa3b, v66
	v_sub_f32_e32 v67, v67, v134
	v_add_f32_e32 v108, v94, v108
	v_exp_f32_e32 v66, v66
	v_mul_f32_e32 v67, 0x3fb8aa3b, v67
	v_sub_f32_e32 v68, v68, v134
	v_add_f32_e32 v108, v95, v108
	v_exp_f32_e32 v67, v67
	v_mul_f32_e32 v68, 0x3fb8aa3b, v68
	v_sub_f32_e32 v69, v69, v134
	v_add_f32_e32 v108, v64, v108
	v_exp_f32_e32 v68, v68
	v_mul_f32_e32 v69, 0x3fb8aa3b, v69
	v_sub_f32_e32 v70, v70, v134
	v_add_f32_e32 v108, v65, v108
	v_exp_f32_e32 v69, v69
	v_mul_f32_e32 v70, 0x3fb8aa3b, v70
	v_sub_f32_e32 v71, v71, v134
	v_add_f32_e32 v108, v66, v108
	v_exp_f32_e32 v70, v70
	v_mul_f32_e32 v71, 0x3fb8aa3b, v71
	v_sub_f32_e32 v72, v72, v134
	v_add_f32_e32 v108, v67, v108
	v_exp_f32_e32 v71, v71
	v_mul_f32_e32 v72, 0x3fb8aa3b, v72
	v_sub_f32_e32 v73, v73, v134
	v_add_f32_e32 v108, v68, v108
	v_exp_f32_e32 v72, v72
	v_mul_f32_e32 v73, 0x3fb8aa3b, v73
	v_sub_f32_e32 v74, v74, v134
	v_add_f32_e32 v108, v69, v108
	v_exp_f32_e32 v73, v73
	v_mul_f32_e32 v74, 0x3fb8aa3b, v74
	v_sub_f32_e32 v75, v75, v134
	v_add_f32_e32 v108, v70, v108
	v_exp_f32_e32 v74, v74
	v_mul_f32_e32 v75, 0x3fb8aa3b, v75
	v_sub_f32_e32 v76, v76, v134
	v_add_f32_e32 v108, v71, v108
	v_exp_f32_e32 v75, v75
	v_mul_f32_e32 v76, 0x3fb8aa3b, v76
	v_sub_f32_e32 v77, v77, v134
	v_add_f32_e32 v108, v72, v108
	v_exp_f32_e32 v76, v76
	v_mul_f32_e32 v77, 0x3fb8aa3b, v77
	v_sub_f32_e32 v78, v78, v134
	v_add_f32_e32 v108, v73, v108
	v_exp_f32_e32 v77, v77
	v_mul_f32_e32 v78, 0x3fb8aa3b, v78
	v_sub_f32_e32 v79, v79, v134
	v_add_f32_e32 v108, v74, v108
	v_exp_f32_e32 v78, v78
	v_mul_f32_e32 v79, 0x3fb8aa3b, v79
	v_sub_f32_e32 v48, v48, v134
	v_add_f32_e32 v108, v75, v108
	v_exp_f32_e32 v79, v79
	v_mul_f32_e32 v48, 0x3fb8aa3b, v48
	v_sub_f32_e32 v49, v49, v134
	v_add_f32_e32 v108, v76, v108
	v_exp_f32_e32 v48, v48
	v_mul_f32_e32 v49, 0x3fb8aa3b, v49
	v_sub_f32_e32 v50, v50, v134
	v_add_f32_e32 v108, v77, v108
	v_exp_f32_e32 v49, v49
; DI void attn_prompt_item(const Params& p, int item, ldsp lds, int tid_) {
;     ...
;   float sum = 0.f;
; #pragma unroll
;   for (int kt = 0; kt < 8; ++kt)
; #pragma unroll
;     for (int i = 0; i < 16; ++i) { const float e = __expf(S[kt][i] - mx); S[kt][i] = e; sum += e; }
	v_mul_f32_e32 v50, 0x3fb8aa3b, v50
	v_sub_f32_e32 v51, v51, v134
	v_add_f32_e32 v108, v78, v108
	v_exp_f32_e32 v50, v50
	v_mul_f32_e32 v51, 0x3fb8aa3b, v51
	v_sub_f32_e32 v52, v52, v134
	v_add_f32_e32 v108, v79, v108
	v_exp_f32_e32 v51, v51
	v_mul_f32_e32 v52, 0x3fb8aa3b, v52
	v_sub_f32_e32 v53, v53, v134
	v_add_f32_e32 v108, v48, v108
	v_exp_f32_e32 v52, v52
	v_mul_f32_e32 v53, 0x3fb8aa3b, v53
	v_sub_f32_e32 v54, v54, v134
	v_add_f32_e32 v108, v49, v108
	v_exp_f32_e32 v53, v53
	v_mul_f32_e32 v54, 0x3fb8aa3b, v54
	v_sub_f32_e32 v55, v55, v134
	v_add_f32_e32 v108, v50, v108
	v_exp_f32_e32 v54, v54
	v_mul_f32_e32 v55, 0x3fb8aa3b, v55
	v_sub_f32_e32 v56, v56, v134
	v_add_f32_e32 v108, v51, v108
	v_exp_f32_e32 v55, v55
	v_mul_f32_e32 v56, 0x3fb8aa3b, v56
	v_sub_f32_e32 v57, v57, v134
	v_add_f32_e32 v108, v52, v108
	v_exp_f32_e32 v56, v56
	v_mul_f32_e32 v57, 0x3fb8aa3b, v57
	v_sub_f32_e32 v58, v58, v134
	v_add_f32_e32 v108, v53, v108
	v_exp_f32_e32 v57, v57
	v_mul_f32_e32 v58, 0x3fb8aa3b, v58
	v_sub_f32_e32 v59, v59, v134
	v_add_f32_e32 v108, v54, v108
	v_exp_f32_e32 v58, v58
	v_mul_f32_e32 v59, 0x3fb8aa3b, v59
	v_sub_f32_e32 v60, v60, v134
	v_add_f32_e32 v108, v55, v108
	v_exp_f32_e32 v59, v59
	v_mul_f32_e32 v60, 0x3fb8aa3b, v60
	v_sub_f32_e32 v61, v61, v134
	v_add_f32_e32 v108, v56, v108
	v_exp_f32_e32 v60, v60
	v_mul_f32_e32 v61, 0x3fb8aa3b, v61
	v_sub_f32_e32 v62, v62, v134
	v_add_f32_e32 v108, v57, v108
	v_exp_f32_e32 v61, v61
	v_mul_f32_e32 v62, 0x3fb8aa3b, v62
	v_sub_f32_e32 v63, v63, v134
	v_sub_f32_e32 v36, v36, v134
	v_add_f32_e32 v108, v58, v108
	v_exp_f32_e32 v62, v62
	v_mul_f32_e32 v63, 0x3fb8aa3b, v63
	v_sub_f32_e32 v32, v32, v134
	v_mul_f32_e32 v36, 0x3fb8aa3b, v36
	v_add_f32_e32 v108, v59, v108
	v_exp_f32_e32 v63, v63
	v_mul_f32_e32 v32, 0x3fb8aa3b, v32
	v_sub_f32_e32 v33, v33, v134
	v_exp_f32_e32 v152, v36
	v_sub_f32_e32 v36, v37, v134
	v_sub_f32_e32 v37, v40, v134
	v_add_f32_e32 v108, v60, v108
	v_exp_f32_e32 v32, v32
	v_mul_f32_e32 v33, 0x3fb8aa3b, v33
	v_sub_f32_e32 v34, v34, v134
	v_mul_f32_e32 v37, 0x3fb8aa3b, v37
	v_add_f32_e32 v108, v61, v108
	v_exp_f32_e32 v33, v33
	v_mul_f32_e32 v34, 0x3fb8aa3b, v34
	v_sub_f32_e32 v35, v35, v134
	v_exp_f32_e32 v156, v37
	v_sub_f32_e32 v37, v41, v134
	v_add_f32_e32 v108, v62, v108
	v_exp_f32_e32 v34, v34
	v_mul_f32_e32 v35, 0x3fb8aa3b, v35
	v_mul_f32_e32 v36, 0x3fb8aa3b, v36
	v_mul_f32_e32 v37, 0x3fb8aa3b, v37
	v_add_f32_e32 v108, v63, v108
	v_exp_f32_e32 v35, v35
	v_exp_f32_e32 v153, v36
	v_sub_f32_e32 v36, v38, v134
	v_exp_f32_e32 v157, v37
	v_sub_f32_e32 v37, v42, v134
	v_add_f32_e32 v108, v32, v108
	v_mul_f32_e32 v36, 0x3fb8aa3b, v36
	v_mul_f32_e32 v37, 0x3fb8aa3b, v37
	v_add_f32_e32 v108, v33, v108
	v_exp_f32_e32 v154, v36
	v_sub_f32_e32 v36, v39, v134
	v_exp_f32_e32 v158, v37
	v_sub_f32_e32 v37, v43, v134
	v_sub_f32_e32 v16, v16, v134
	v_add_f32_e32 v108, v34, v108
	v_mul_f32_e32 v36, 0x3fb8aa3b, v36
	v_mul_f32_e32 v37, 0x3fb8aa3b, v37
	v_mul_f32_e32 v16, 0x3fb8aa3b, v16
	v_add_f32_e32 v108, v35, v108
	v_exp_f32_e32 v155, v36
	v_exp_f32_e32 v159, v37
	v_sub_f32_e32 v37, v44, v134
	v_exp_f32_e32 v210, v16
	v_sub_f32_e32 v16, v17, v134
	v_sub_f32_e32 v17, v20, v134
	v_add_f32_e32 v36, v152, v108
	v_mul_f32_e32 v37, 0x3fb8aa3b, v37
	v_mul_f32_e32 v17, 0x3fb8aa3b, v17
	v_add_f32_e32 v36, v153, v36
	v_exp_f32_e32 v166, v37
	v_sub_f32_e32 v37, v45, v134
	v_exp_f32_e32 v216, v17
	v_sub_f32_e32 v17, v21, v134
	v_add_f32_e32 v36, v154, v36
	v_mul_f32_e32 v37, 0x3fb8aa3b, v37
	v_mul_f32_e32 v17, 0x3fb8aa3b, v17
	v_add_f32_e32 v36, v155, v36
	v_exp_f32_e32 v167, v37
	v_sub_f32_e32 v37, v46, v134
	v_exp_f32_e32 v217, v17
	v_sub_f32_e32 v17, v22, v134
	v_add_f32_e32 v36, v156, v36
	v_mul_f32_e32 v37, 0x3fb8aa3b, v37
	v_mul_f32_e32 v17, 0x3fb8aa3b, v17
	v_add_f32_e32 v36, v157, v36
	v_exp_f32_e32 v208, v37
	v_sub_f32_e32 v37, v47, v134
	v_exp_f32_e32 v218, v17
	v_sub_f32_e32 v17, v23, v134
	v_add_f32_e32 v36, v158, v36
	v_mul_f32_e32 v37, 0x3fb8aa3b, v37
	v_mul_f32_e32 v16, 0x3fb8aa3b, v16
	v_mul_f32_e32 v17, 0x3fb8aa3b, v17
	v_add_f32_e32 v36, v159, v36
	v_exp_f32_e32 v209, v37
	v_exp_f32_e32 v211, v16
	v_sub_f32_e32 v16, v18, v134
	v_exp_f32_e32 v219, v17
	v_sub_f32_e32 v17, v24, v134
	v_add_f32_e32 v36, v166, v36
	v_mul_f32_e32 v16, 0x3fb8aa3b, v16
	v_mul_f32_e32 v17, 0x3fb8aa3b, v17
	v_add_f32_e32 v36, v167, v36
	v_exp_f32_e32 v214, v16
	v_sub_f32_e32 v16, v19, v134
	v_exp_f32_e32 v220, v17
	v_sub_f32_e32 v17, v25, v134
	v_add_f32_e32 v36, v208, v36
	v_mul_f32_e32 v16, 0x3fb8aa3b, v16
	v_mul_f32_e32 v17, 0x3fb8aa3b, v17
	v_add_f32_e32 v36, v209, v36
	v_exp_f32_e32 v215, v16
	v_exp_f32_e32 v221, v17
	v_sub_f32_e32 v17, v26, v134
	v_add_f32_e32 v16, v210, v36
	v_mul_f32_e32 v17, 0x3fb8aa3b, v17
	v_add_f32_e32 v16, v211, v16
	v_exp_f32_e32 v222, v17
	v_sub_f32_e32 v17, v27, v134
	v_sub_f32_e32 v0, v0, v134
	v_add_f32_e32 v16, v214, v16
	v_mul_f32_e32 v17, 0x3fb8aa3b, v17
	v_mul_f32_e32 v0, 0x3fb8aa3b, v0
	v_add_f32_e32 v16, v215, v16
	v_exp_f32_e32 v223, v17
	v_sub_f32_e32 v17, v28, v134
	v_exp_f32_e32 v228, v0
	v_sub_f32_e32 v0, v1, v134
	v_sub_f32_e32 v1, v4, v134
	v_add_f32_e32 v16, v216, v16
	v_mul_f32_e32 v17, 0x3fb8aa3b, v17
	v_mul_f32_e32 v1, 0x3fb8aa3b, v1
	v_add_f32_e32 v16, v217, v16
	v_exp_f32_e32 v224, v17
	v_sub_f32_e32 v17, v29, v134
	v_exp_f32_e32 v232, v1
	v_sub_f32_e32 v1, v5, v134
	v_add_f32_e32 v16, v218, v16
	v_mul_f32_e32 v17, 0x3fb8aa3b, v17
	v_mul_f32_e32 v1, 0x3fb8aa3b, v1
	v_add_f32_e32 v16, v219, v16
	v_exp_f32_e32 v225, v17
	v_sub_f32_e32 v17, v30, v134
	v_exp_f32_e32 v233, v1
	v_sub_f32_e32 v1, v6, v134
	v_add_f32_e32 v16, v220, v16
	v_mul_f32_e32 v17, 0x3fb8aa3b, v17
; #define LAS __attribute__((address_space(3)))
; DI unsigned pk2(float lo, float hi) { f32x2 v = {lo, hi}; return __builtin_bit_cast(unsigned, __builtin_convertvector(v, bf16x2v)); }
; DI void attn_prompt_item(const Params& p, int item, ldsp lds, int tid_) {
;     ...
;   sum += __shfl_xor(sum, 32);
;   const float inv = 1.f / sum;
;   bf16x8 pb[8][2];
; #pragma unroll
;   for (int kt = 0; kt < 8; ++kt)
; #pragma unroll
;     for (int s = 0; s < 2; ++s) {
;       u32x4 pw; pw.x = pk2(S[kt][8 * s], S[kt][8 * s + 1]); pw.y = pk2(S[kt][8 * s + 2], S[kt][8 * s + 3]); pw.z = pk2(S[kt][8 * s + 4], S[kt][8 * s + 5]); pw.w = pk2(S[kt][8 * s + 6], S[kt][8 * s + 7]);
;       pb[kt][s] = __builtin_bit_cast(bf16x8, pw);
;     }
;   __syncthreads();
; #pragma unroll
;   for (int hb = 0; hb < 2; ++hb) {
;     u32x4 vp[8];
; #pragma unroll
;     for (int i = 0; i < 8; ++i) { const int idx = tid + 512 * (hb * 8 + i), d = idx >> 5, c = idx & 31; vp[i] = ld16(mvt + ((size_t)((b * 4 + h) * 256 + d)) * 256 + c * 8); }
; #pragma unroll
;     for (int i = 0; i < 8; ++i) { const int idx = tid + 512 * (hb * 8 + i), d = idx >> 5, c = idx & 31; *(LAS u32x4*)(lds + d * 512 + ((c ^ (d & 15)) * 16)) = vp[i]; }
;   }
;   __syncthreads();
	v_mul_f32_e32 v1, 0x3fb8aa3b, v1
	v_add_f32_e32 v16, v221, v16
	v_exp_f32_e32 v226, v17
	v_sub_f32_e32 v17, v31, v134
	v_exp_f32_e32 v234, v1
	v_sub_f32_e32 v1, v7, v134
	v_add_f32_e32 v16, v222, v16
	v_mul_f32_e32 v17, 0x3fb8aa3b, v17
	v_mul_f32_e32 v0, 0x3fb8aa3b, v0
	v_mul_f32_e32 v1, 0x3fb8aa3b, v1
	v_add_f32_e32 v16, v223, v16
	v_exp_f32_e32 v227, v17
	v_exp_f32_e32 v229, v0
	v_sub_f32_e32 v0, v2, v134
	v_exp_f32_e32 v235, v1
	v_sub_f32_e32 v1, v8, v134
	v_add_f32_e32 v16, v224, v16
	v_mul_f32_e32 v0, 0x3fb8aa3b, v0
	v_mul_f32_e32 v1, 0x3fb8aa3b, v1
	v_add_f32_e32 v16, v225, v16
	v_exp_f32_e32 v230, v0
	v_sub_f32_e32 v0, v3, v134
	v_exp_f32_e32 v236, v1
	v_sub_f32_e32 v1, v9, v134
	v_add_f32_e32 v16, v226, v16
	v_mul_f32_e32 v0, 0x3fb8aa3b, v0
	v_mul_f32_e32 v1, 0x3fb8aa3b, v1
	v_add_f32_e32 v16, v227, v16
	v_exp_f32_e32 v231, v0
	v_exp_f32_e32 v237, v1
	v_sub_f32_e32 v1, v10, v134
	v_add_f32_e32 v0, v228, v16
	v_mul_f32_e32 v1, 0x3fb8aa3b, v1
	v_add_f32_e32 v0, v229, v0
	v_exp_f32_e32 v238, v1
	v_sub_f32_e32 v1, v11, v134
	v_add_f32_e32 v0, v230, v0
	v_mul_f32_e32 v1, 0x3fb8aa3b, v1
	v_add_f32_e32 v0, v231, v0
	v_exp_f32_e32 v239, v1
	v_sub_f32_e32 v1, v12, v134
	v_add_f32_e32 v0, v232, v0
	v_mul_f32_e32 v1, 0x3fb8aa3b, v1
	v_add_f32_e32 v0, v233, v0
	v_exp_f32_e32 v240, v1
	v_sub_f32_e32 v1, v13, v134
	v_add_f32_e32 v0, v234, v0
	v_mul_f32_e32 v1, 0x3fb8aa3b, v1
	v_add_f32_e32 v0, v235, v0
	v_exp_f32_e32 v241, v1
	v_sub_f32_e32 v1, v14, v134
	v_add_f32_e32 v0, v236, v0
	v_mul_f32_e32 v1, 0x3fb8aa3b, v1
	v_add_f32_e32 v0, v237, v0
	v_exp_f32_e32 v242, v1
	v_sub_f32_e32 v1, v15, v134
	v_add_f32_e32 v0, v238, v0
	v_mul_f32_e32 v1, 0x3fb8aa3b, v1
	v_add_f32_e32 v0, v239, v0
	v_exp_f32_e32 v243, v1
	v_add_f32_e32 v0, v240, v0
	v_add_f32_e32 v0, v241, v0
	v_add_f32_e32 v0, v242, v0
	v_add_f32_e32 v0, v243, v0
	ds_bpermute_b32 v1, v132, v0
	v_add_u32_e32 v2, s3, v177
	v_add_u32_e32 v8, s3, v178
	v_add_u32_e32 v10, s3, v180
	v_add_u32_e32 v16, s3, v181
	s_waitcnt lgkmcnt(0)
	v_add_f32_e32 v244, v0, v1
	v_add_u32_e32 v0, s3, v176
	v_add_u32_e32 v18, s3, v183
	v_add_u32_e32 v24, s3, v184
	v_add_u32_e32 v26, s3, v186
	v_add_u32_e32 v36, s3, v195
	v_add_u32_e32 v38, s3, v197
	v_add_u32_e32 v44, s3, v199
	v_add_u32_e32 v46, s3, v201
	v_ashrrev_i32_e32 v1, 31, v0
	v_ashrrev_i32_e32 v3, 31, v2
	v_ashrrev_i32_e32 v9, 31, v8
	v_ashrrev_i32_e32 v11, 31, v10
	v_ashrrev_i32_e32 v17, 31, v16
	v_ashrrev_i32_e32 v19, 31, v18
	v_ashrrev_i32_e32 v25, 31, v24
	v_ashrrev_i32_e32 v27, 31, v26
	v_ashrrev_i32_e32 v37, 31, v36
	v_ashrrev_i32_e32 v39, 31, v38
	v_ashrrev_i32_e32 v45, 31, v44
	v_ashrrev_i32_e32 v47, 31, v46
	v_lshl_add_u64 v[122:123], s[6:7], 0, v[164:165]
	v_lshlrev_b64 v[0:1], 9, v[0:1]
	v_lshlrev_b64 v[2:3], 9, v[2:3]
	v_lshlrev_b64 v[8:9], 9, v[8:9]
	v_lshlrev_b64 v[10:11], 9, v[10:11]
	v_lshlrev_b64 v[16:17], 9, v[16:17]
	v_lshlrev_b64 v[18:19], 9, v[18:19]
	v_lshlrev_b64 v[24:25], 9, v[24:25]
	v_lshlrev_b64 v[26:27], 9, v[26:27]
	v_lshlrev_b64 v[36:37], 9, v[36:37]
	v_lshlrev_b64 v[38:39], 9, v[38:39]
	v_lshlrev_b64 v[44:45], 9, v[44:45]
	v_lshlrev_b64 v[46:47], 9, v[46:47]
	v_lshl_add_u64 v[0:1], v[122:123], 0, v[0:1]
	v_lshl_add_u64 v[4:5], v[122:123], 0, v[2:3]
	v_lshl_add_u64 v[8:9], v[122:123], 0, v[8:9]
	v_lshl_add_u64 v[12:13], v[122:123], 0, v[10:11]
	v_lshl_add_u64 v[16:17], v[122:123], 0, v[16:17]
	v_lshl_add_u64 v[20:21], v[122:123], 0, v[18:19]
	v_lshl_add_u64 v[24:25], v[122:123], 0, v[24:25]
	v_lshl_add_u64 v[28:29], v[122:123], 0, v[26:27]
	v_lshl_add_u64 v[36:37], v[122:123], 0, v[36:37]
	v_lshl_add_u64 v[40:41], v[122:123], 0, v[38:39]
	v_lshl_add_u64 v[44:45], v[122:123], 0, v[44:45]
	v_lshl_add_u64 v[124:125], v[122:123], 0, v[46:47]
	v_cvt_pk_bf16_f32 v108, v133, v135
	global_load_dwordx4 v[0:3], v[0:1], off
	s_nop 0
	global_load_dwordx4 v[4:7], v[4:5], off
	s_nop 0
	global_load_dwordx4 v[8:11], v[8:9], off
	s_nop 0
	global_load_dwordx4 v[12:15], v[12:13], off
	s_nop 0
	global_load_dwordx4 v[16:19], v[16:17], off
	s_nop 0
	global_load_dwordx4 v[20:23], v[20:21], off
	s_nop 0
	global_load_dwordx4 v[24:27], v[24:25], off
	s_nop 0
	global_load_dwordx4 v[28:31], v[28:29], off
	s_nop 0
	global_load_dwordx4 v[36:39], v[36:37], off
	s_nop 0
	global_load_dwordx4 v[40:43], v[40:41], off
	s_nop 0
	global_load_dwordx4 v[44:47], v[44:45], off
	s_nop 0
	global_load_dwordx4 v[132:135], v[124:125], off
	v_add_u32_e32 v124, s3, v203
	v_ashrrev_i32_e32 v125, 31, v124
	v_add_u32_e32 v126, s3, v204
	v_lshlrev_b64 v[124:125], 9, v[124:125]
	v_ashrrev_i32_e32 v127, 31, v126
	v_lshl_add_u64 v[124:125], v[122:123], 0, v[124:125]
	v_lshlrev_b64 v[126:127], 9, v[126:127]
	v_cvt_pk_bf16_f32 v109, v136, v137
	v_cvt_pk_bf16_f32 v110, v138, v139
	v_lshl_add_u64 v[126:127], v[122:123], 0, v[126:127]
	global_load_dwordx4 v[136:139], v[124:125], off
	global_load_dwordx4 v[140:143], v[126:127], off
	v_add_u32_e32 v124, s3, v206
	v_ashrrev_i32_e32 v125, 31, v124
	v_add_u32_e32 v126, s3, v207
	v_lshlrev_b64 v[124:125], 9, v[124:125]
	v_ashrrev_i32_e32 v127, 31, v126
	v_lshl_add_u64 v[124:125], v[122:123], 0, v[124:125]
	v_lshlrev_b64 v[126:127], 9, v[126:127]
	v_lshl_add_u64 v[122:123], v[122:123], 0, v[126:127]
	global_load_dwordx4 v[144:147], v[124:125], off
	global_load_dwordx4 v[148:151], v[122:123], off
	s_waitcnt vmcnt(15)
	ds_write_b128 v179, v[0:3]
	s_waitcnt vmcnt(14)
	ds_write_b128 v182, v[4:7]
	s_waitcnt vmcnt(13)
	ds_write_b128 v185, v[8:11]
	s_waitcnt vmcnt(12)
	ds_write_b128 v187, v[12:15]
	s_waitcnt vmcnt(11)
	ds_write_b128 v188, v[16:19]
	s_waitcnt vmcnt(10)
	ds_write_b128 v189, v[20:23]
	s_waitcnt vmcnt(9)
	ds_write_b128 v190, v[24:27]
	s_waitcnt vmcnt(8)
	ds_write_b128 v191, v[28:31]
	s_waitcnt vmcnt(7)
	ds_write_b128 v192, v[36:39]
	s_waitcnt vmcnt(6)
	ds_write_b128 v193, v[40:43]
	s_waitcnt vmcnt(5)
	ds_write_b128 v194, v[44:47]
	s_waitcnt vmcnt(4)
	ds_write_b128 v196, v[132:135]
	s_waitcnt vmcnt(3)
	ds_write_b128 v200, v[136:139]
	v_div_scale_f32 v12, s[28:29], v244, v244, 1.0
	v_rcp_f32_e32 v13, v12
	s_waitcnt vmcnt(2)
	ds_write_b128 v198, v[140:143]
	s_waitcnt vmcnt(1)
	ds_write_b128 v202, v[144:147]
	s_waitcnt vmcnt(0)
	ds_write_b128 v205, v[148:151]
	v_and_b32_e32 v146, 0xf0, v174
	v_bitop3_b32 v139, v174, 16, v171 bitop3:0x6c
	v_fma_f32 v0, -v12, v13, 1.0
	v_add3_u32 v14, v173, v146, v160
	v_add3_u32 v15, v173, v139, v160
	v_fmac_f32_e32 v13, v0, v13
	s_waitcnt lgkmcnt(0)
	s_barrier
; #define LAS __attribute__((address_space(3)))
; DI unsigned pk2(float lo, float hi) { f32x2 v = {lo, hi}; return __builtin_bit_cast(unsigned, __builtin_convertvector(v, bf16x2v)); }
; DI void attn_prompt_item(const Params& p, int item, ldsp lds, int tid_) {
;     ...
;   bf16x8 pb[8][2];
; #pragma unroll
;   for (int kt = 0; kt < 8; ++kt)
; #pragma unroll
;     for (int s = 0; s < 2; ++s) {
;       u32x4 pw; pw.x = pk2(S[kt][8 * s], S[kt][8 * s + 1]); pw.y = pk2(S[kt][8 * s + 2], S[kt][8 * s + 3]); pw.z = pk2(S[kt][8 * s + 4], S[kt][8 * s + 5]); pw.w = pk2(S[kt][8 * s + 6], S[kt][8 * s + 7]);
;       pb[kt][s] = __builtin_bit_cast(bf16x8, pw);
;     }
;   __syncthreads();
; #pragma unroll
;   for (int hb = 0; hb < 2; ++hb) {
;     u32x4 vp[8];
; #pragma unroll
;     for (int i = 0; i < 8; ++i) { const int idx = tid + 512 * (hb * 8 + i), d = idx >> 5, c = idx & 31; vp[i] = ld16(mvt + ((size_t)((b * 4 + h) * 256 + d)) * 256 + c * 8); }
; #pragma unroll
;     for (int i = 0; i < 8; ++i) { const int idx = tid + 512 * (hb * 8 + i), d = idx >> 5, c = idx & 31; *(LAS u32x4*)(lds + d * 512 + ((c ^ (d & 15)) * 16)) = vp[i]; }
;   }
;   __syncthreads();
; #pragma unroll
;   for (int dh = 0; dh < 2; ++dh) {
;     f32x16 O[4];
; #pragma unroll
;     for (int dt = 0; dt < 4; ++dt)
; #pragma unroll
;       for (int i = 0; i < 16; ++i) O[dt][i] = 0.f;
;     {
;       u32x2 va[4][2], vb[4][2];
;     ...
; #pragma unroll
;       for (int dt = 0; dt < 4; ++dt) { va[dt][0] = *(const LAS u32x2*)VF_ADDR(0, dt, 0); va[dt][1] = *(const LAS u32x2*)VF_ADDR(0, dt, 1); }
; #pragma unroll
;       for (int gi = 0; gi < 16; ++gi) {
;         if (gi + 1 < 16) {
; #pragma unroll
;           for (int dt = 0; dt < 4; ++dt) {
;             if (gi & 1) { va[dt][0] = *(const LAS u32x2*)VF_ADDR(gi + 1, dt, 0); va[dt][1] = *(const LAS u32x2*)VF_ADDR(gi + 1, dt, 1); }
;             else { vb[dt][0] = *(const LAS u32x2*)VF_ADDR(gi + 1, dt, 0); vb[dt][1] = *(const LAS u32x2*)VF_ADDR(gi + 1, dt, 1); } } }
; #pragma unroll
;         for (int dt = 0; dt < 4; ++dt) { const u32x2 lo = (gi & 1) ? vb[dt][0] : va[dt][0], hi = (gi & 1) ? vb[dt][1] : va[dt][1];
;           u32x4 vw; vw.x = lo.x; vw.y = lo.y; vw.z = hi.x; vw.w = hi.y;
;           O[dt] = __builtin_amdgcn_mfma_f32_32x32x16_bf16(__builtin_bit_cast(bf16x8, vw), pb[gi >> 1][gi & 1], O[dt], 0, 0, 0); }
;         __builtin_amdgcn_sched_barrier(0);
;       }
	ds_read2st64_b64 v[0:3], v14 offset1:32
	ds_read2st64_b64 v[4:7], v15 offset1:32
	v_div_scale_f32 v16, vcc, 1.0, v244, 1.0
	v_cvt_pk_bf16_f32 v111, v112, v113
	s_waitcnt lgkmcnt(1)
	v_mov_b32_e32 v8, v0
	v_mov_b32_e32 v9, v1
	s_waitcnt lgkmcnt(0)
	v_mov_b32_e32 v10, v4
	v_mov_b32_e32 v11, v5
	v_mul_f32_e32 v0, v16, v13
	v_fma_f32 v1, -v12, v0, v16
	v_fmac_f32_e32 v0, v1, v13
	v_fma_f32 v1, -v12, v0, v16
	v_cvt_pk_bf16_f32 v125, v116, v117
	v_cvt_pk_bf16_f32 v116, v104, v105
	v_cvt_pk_bf16_f32 v117, v106, v107
	v_cvt_pk_bf16_f32 v104, v88, v89
	v_cvt_pk_bf16_f32 v105, v90, v91
	v_cvt_pk_bf16_f32 v106, v92, v93
	v_cvt_pk_bf16_f32 v107, v94, v95
	v_cvt_pk_bf16_f32 v92, v48, v49
	v_cvt_pk_bf16_f32 v93, v50, v51
	v_cvt_pk_bf16_f32 v94, v52, v53
	v_cvt_pk_bf16_f32 v95, v54, v55
	v_cvt_pk_bf16_f32 v88, v56, v57
	v_cvt_pk_bf16_f32 v89, v58, v59
	v_cvt_pk_bf16_f32 v90, v60, v61
	v_cvt_pk_bf16_f32 v91, v62, v63
	v_mfma_f32_32x32x16_bf16 v[48:63], v[8:11], v[108:111], 0
	ds_read2st64_b64 v[8:11], v14 offset0:64 offset1:96
	v_mov_b32_e32 v4, v2
	v_mov_b32_e32 v5, v3
	v_div_fmas_f32 v12, v1, v13, v0
	ds_read2st64_b64 v[0:3], v15 offset0:64 offset1:96
	v_cvt_pk_bf16_f32 v126, v118, v119
	v_cvt_pk_bf16_f32 v118, v128, v129
	v_lshlrev_b32_e32 v129, 4, v175
	v_xor_b32_e32 v147, 32, v129
	v_xor_b32_e32 v148, 48, v129
	v_cvt_pk_bf16_f32 v112, v80, v81
	v_cvt_pk_bf16_f32 v81, v158, v159
	v_add3_u32 v149, v173, v147, v160
	v_add3_u32 v158, v173, v148, v160
	v_cvt_pk_bf16_f32 v124, v114, v115
	v_cvt_pk_bf16_f32 v119, v130, v131
	v_cvt_pk_bf16_f32 v115, v86, v87
	v_cvt_pk_bf16_f32 v86, v152, v153
	ds_read2st64_b64 v[130:133], v149 offset1:32
	ds_read2st64_b64 v[134:137], v158 offset1:32
	ds_read2st64_b64 v[140:143], v149 offset0:64 offset1:96
	ds_read2st64_b64 v[150:153], v158 offset0:64 offset1:96
	v_cvt_pk_bf16_f32 v114, v84, v85
	v_cvt_pk_bf16_f32 v84, v32, v33
	v_cvt_pk_bf16_f32 v85, v34, v35
	v_mfma_f32_32x32x16_bf16 v[32:47], v[4:7], v[108:111], 0
	s_waitcnt lgkmcnt(5)
	v_mov_b32_e32 v4, v8
	v_mov_b32_e32 v5, v9
	s_waitcnt lgkmcnt(4)
	v_mov_b32_e32 v6, v0
	v_mov_b32_e32 v7, v1
	v_mov_b32_e32 v0, v10
	v_mov_b32_e32 v1, v11
	v_cvt_pk_bf16_f32 v127, v120, v121
	v_cvt_pk_bf16_f32 v120, v96, v97
	v_cvt_pk_bf16_f32 v121, v98, v99
	v_cvt_pk_bf16_f32 v122, v100, v101
	v_cvt_pk_bf16_f32 v123, v102, v103
	v_cvt_pk_bf16_f32 v113, v82, v83
	v_cvt_pk_bf16_f32 v100, v64, v65
	v_cvt_pk_bf16_f32 v101, v66, v67
	v_cvt_pk_bf16_f32 v102, v68, v69
	v_cvt_pk_bf16_f32 v103, v70, v71
	v_cvt_pk_bf16_f32 v96, v72, v73
	v_cvt_pk_bf16_f32 v97, v74, v75
	v_cvt_pk_bf16_f32 v98, v76, v77
	v_cvt_pk_bf16_f32 v99, v78, v79
	v_cvt_pk_bf16_f32 v87, v154, v155
	v_cvt_pk_bf16_f32 v80, v156, v157
	v_cvt_pk_bf16_f32 v82, v166, v167
	v_cvt_pk_bf16_f32 v83, v208, v209
	v_cvt_pk_bf16_f32 v76, v210, v211
	v_cvt_pk_bf16_f32 v77, v214, v215
	v_cvt_pk_bf16_f32 v78, v216, v217
	v_cvt_pk_bf16_f32 v79, v218, v219
	v_cvt_pk_bf16_f32 v72, v220, v221
	v_cvt_pk_bf16_f32 v73, v222, v223
	v_cvt_pk_bf16_f32 v74, v224, v225
	v_cvt_pk_bf16_f32 v75, v226, v227
	v_cvt_pk_bf16_f32 v68, v228, v229
	v_cvt_pk_bf16_f32 v69, v230, v231
	v_cvt_pk_bf16_f32 v70, v232, v233
	v_cvt_pk_bf16_f32 v71, v234, v235
	v_cvt_pk_bf16_f32 v64, v236, v237
	v_cvt_pk_bf16_f32 v65, v238, v239
	v_cvt_pk_bf16_f32 v66, v240, v241
	v_cvt_pk_bf16_f32 v67, v242, v243
	v_div_fixup_f32 v128, v12, v244, 1.0
	v_mfma_f32_32x32x16_bf16 v[16:31], v[4:7], v[108:111], 0
	v_mfma_f32_32x32x16_bf16 v[0:15], v[0:3], v[108:111], 0
	s_waitcnt lgkmcnt(3)
	v_mov_b32_e32 v154, v130
	v_mov_b32_e32 v155, v131
	s_waitcnt lgkmcnt(2)
	v_mov_b32_e32 v156, v134
	v_mov_b32_e32 v157, v135
	v_mov_b32_e32 v134, v132
	v_mov_b32_e32 v135, v133
	s_waitcnt lgkmcnt(1)
	v_mov_b32_e32 v130, v140
	v_mov_b32_e32 v131, v141
	s_waitcnt lgkmcnt(0)
	v_mov_b32_e32 v132, v150
	v_mov_b32_e32 v133, v151
	v_xor_b32_e32 v144, 64, v129
	v_xor_b32_e32 v145, 0x50, v129
	v_add3_u32 v159, v173, v144, v160
	v_add3_u32 v182, v173, v145, v160
	v_mfma_f32_32x32x16_bf16 v[48:63], v[154:157], v[124:127], v[48:63]
	v_mov_b32_e32 v150, v142
	v_mov_b32_e32 v151, v143
	v_mfma_f32_32x32x16_bf16 v[32:47], v[134:137], v[124:127], v[32:47]
	v_mfma_f32_32x32x16_bf16 v[16:31], v[130:133], v[124:127], v[16:31]
	ds_read2st64_b64 v[130:133], v159 offset1:32
	ds_read2st64_b64 v[134:137], v182 offset1:32
	ds_read2st64_b64 v[154:157], v159 offset0:64 offset1:96
	ds_read2st64_b64 v[164:167], v182 offset0:64 offset1:96
	v_mfma_f32_32x32x16_bf16 v[0:15], v[150:153], v[124:127], v[0:15]
	s_waitcnt lgkmcnt(3)
	v_mov_b32_e32 v140, v130
	v_mov_b32_e32 v141, v131
	s_waitcnt lgkmcnt(2)
	v_mov_b32_e32 v142, v134
	v_mov_b32_e32 v143, v135
	v_mov_b32_e32 v134, v132
	v_mov_b32_e32 v135, v133
	s_waitcnt lgkmcnt(1)
	v_mov_b32_e32 v130, v154
	v_mov_b32_e32 v131, v155
	s_waitcnt lgkmcnt(0)
	v_mov_b32_e32 v132, v164
	v_mov_b32_e32 v133, v165
	v_mfma_f32_32x32x16_bf16 v[48:63], v[140:143], v[120:123], v[48:63]
	v_xor_b32_e32 v142, 0x60, v129
	v_xor_b32_e32 v143, 0x70, v129
	v_add3_u32 v183, v173, v142, v160
	v_add3_u32 v184, v173, v143, v160
	v_mov_b32_e32 v164, v156
	v_mov_b32_e32 v165, v157
	v_mfma_f32_32x32x16_bf16 v[32:47], v[134:137], v[120:123], v[32:47]
	v_mfma_f32_32x32x16_bf16 v[16:31], v[130:133], v[120:123], v[16:31]
	ds_read2st64_b64 v[130:133], v183 offset1:32
	ds_read2st64_b64 v[134:137], v184 offset1:32
	ds_read2st64_b64 v[150:153], v183 offset0:64 offset1:96
	ds_read2st64_b64 v[154:157], v184 offset0:64 offset1:96
	v_mfma_f32_32x32x16_bf16 v[0:15], v[164:167], v[120:123], v[0:15]
	s_waitcnt lgkmcnt(3)
	v_mov_b32_e32 v164, v130
	v_mov_b32_e32 v165, v131
	s_waitcnt lgkmcnt(2)
; #define LAS __attribute__((address_space(3)))
; DI void attn_prompt_item(const Params& p, int item, ldsp lds, int tid_) {
;     ...
;     {
;       u32x2 va[4][2], vb[4][2];
;     ...
; #pragma unroll
;       for (int dt = 0; dt < 4; ++dt) { va[dt][0] = *(const LAS u32x2*)VF_ADDR(0, dt, 0); va[dt][1] = *(const LAS u32x2*)VF_ADDR(0, dt, 1); }
; #pragma unroll
;       for (int gi = 0; gi < 16; ++gi) {
;         if (gi + 1 < 16) {
; #pragma unroll
;           for (int dt = 0; dt < 4; ++dt) {
;             if (gi & 1) { va[dt][0] = *(const LAS u32x2*)VF_ADDR(gi + 1, dt, 0); va[dt][1] = *(const LAS u32x2*)VF_ADDR(gi + 1, dt, 1); }
;             else { vb[dt][0] = *(const LAS u32x2*)VF_ADDR(gi + 1, dt, 0); vb[dt][1] = *(const LAS u32x2*)VF_ADDR(gi + 1, dt, 1); } } }
; #pragma unroll
;         for (int dt = 0; dt < 4; ++dt) { const u32x2 lo = (gi & 1) ? vb[dt][0] : va[dt][0], hi = (gi & 1) ? vb[dt][1] : va[dt][1];
;           u32x4 vw; vw.x = lo.x; vw.y = lo.y; vw.z = hi.x; vw.w = hi.y;
;           O[dt] = __builtin_amdgcn_mfma_f32_32x32x16_bf16(__builtin_bit_cast(bf16x8, vw), pb[gi >> 1][gi & 1], O[dt], 0, 0, 0); }
;         __builtin_amdgcn_sched_barrier(0);
;       }
	v_mov_b32_e32 v166, v134
	v_mov_b32_e32 v167, v135
	v_mov_b32_e32 v134, v132
	v_mov_b32_e32 v135, v133
	s_waitcnt lgkmcnt(1)
	v_mov_b32_e32 v130, v150
	v_mov_b32_e32 v131, v151
	s_waitcnt lgkmcnt(0)
	v_mov_b32_e32 v132, v154
	v_mov_b32_e32 v133, v155
	v_xor_b32_e32 v140, 0x80, v129
	v_xor_b32_e32 v141, 0x90, v129
	v_add3_u32 v185, v173, v140, v160
	v_add3_u32 v186, v173, v141, v160
	v_mfma_f32_32x32x16_bf16 v[48:63], v[164:167], v[116:119], v[48:63]
	v_mov_b32_e32 v154, v152
	v_mov_b32_e32 v155, v153
	v_mfma_f32_32x32x16_bf16 v[32:47], v[134:137], v[116:119], v[32:47]
	v_mfma_f32_32x32x16_bf16 v[16:31], v[130:133], v[116:119], v[16:31]
	ds_read2st64_b64 v[130:133], v185 offset1:32
	ds_read2st64_b64 v[134:137], v186 offset1:32
	ds_read2st64_b64 v[150:153], v185 offset0:64 offset1:96
	ds_read2st64_b64 v[164:167], v186 offset0:64 offset1:96
	v_mfma_f32_32x32x16_bf16 v[0:15], v[154:157], v[116:119], v[0:15]
	s_waitcnt lgkmcnt(2)
	v_mov_b32_e32 v156, v134
	v_mov_b32_e32 v157, v135
	v_mov_b32_e32 v134, v132
	v_mov_b32_e32 v135, v133
	v_mov_b32_e32 v154, v130
	v_mov_b32_e32 v155, v131
	s_waitcnt lgkmcnt(1)
	v_mov_b32_e32 v130, v150
	v_mov_b32_e32 v131, v151
	s_waitcnt lgkmcnt(0)
	v_mov_b32_e32 v132, v164
	v_mov_b32_e32 v133, v165
	v_mfma_f32_32x32x16_bf16 v[32:47], v[134:137], v[112:115], v[32:47]
	v_xor_b32_e32 v137, 0xa0, v129
	v_xor_b32_e32 v138, 0xb0, v129
	v_add3_u32 v187, v173, v137, v160
	v_add3_u32 v188, v173, v138, v160
	v_mov_b32_e32 v164, v152
	v_mov_b32_e32 v165, v153
	v_mfma_f32_32x32x16_bf16 v[48:63], v[154:157], v[112:115], v[48:63]
	v_mfma_f32_32x32x16_bf16 v[16:31], v[130:133], v[112:115], v[16:31]
	ds_read2st64_b64 v[130:133], v187 offset1:32
	ds_read2st64_b64 v[150:153], v188 offset1:32
	ds_read2st64_b64 v[154:157], v187 offset0:64 offset1:96
	ds_read2st64_b64 v[174:177], v188 offset0:64 offset1:96
	v_mfma_f32_32x32x16_bf16 v[0:15], v[164:167], v[112:115], v[0:15]
	s_waitcnt lgkmcnt(3)
	v_mov_b32_e32 v164, v130
	v_mov_b32_e32 v165, v131
	s_waitcnt lgkmcnt(2)
	v_mov_b32_e32 v166, v150
	v_mov_b32_e32 v167, v151
	v_mov_b32_e32 v150, v132
	v_mov_b32_e32 v151, v133
	s_waitcnt lgkmcnt(1)
	v_mov_b32_e32 v130, v154
	v_mov_b32_e32 v131, v155
	s_waitcnt lgkmcnt(0)
	v_mov_b32_e32 v132, v174
	v_mov_b32_e32 v133, v175
	v_xor_b32_e32 v135, 0xc0, v129
	v_xor_b32_e32 v136, 0xd0, v129
	v_add3_u32 v189, v173, v135, v160
	v_add3_u32 v190, v173, v136, v160
	v_mfma_f32_32x32x16_bf16 v[48:63], v[164:167], v[104:107], v[48:63]
	v_mov_b32_e32 v174, v156
	v_mov_b32_e32 v175, v157
	v_mfma_f32_32x32x16_bf16 v[32:47], v[150:153], v[104:107], v[32:47]
	v_mfma_f32_32x32x16_bf16 v[16:31], v[130:133], v[104:107], v[16:31]
	ds_read2st64_b64 v[130:133], v189 offset1:32
	ds_read2st64_b64 v[150:153], v190 offset1:32
	ds_read2st64_b64 v[154:157], v189 offset0:64 offset1:96
	ds_read2st64_b64 v[164:167], v190 offset0:64 offset1:96
	v_mfma_f32_32x32x16_bf16 v[0:15], v[174:177], v[104:107], v[0:15]
	s_waitcnt lgkmcnt(2)
	v_mov_b32_e32 v176, v150
	v_mov_b32_e32 v177, v151
	v_mov_b32_e32 v150, v132
	v_mov_b32_e32 v151, v133
	v_mov_b32_e32 v174, v130
	v_mov_b32_e32 v175, v131
	v_mfma_f32_32x32x16_bf16 v[32:47], v[150:153], v[100:103], v[32:47]
	s_waitcnt lgkmcnt(1)
	v_mov_b32_e32 v150, v154
	v_mov_b32_e32 v151, v155
	s_waitcnt lgkmcnt(0)
	v_mov_b32_e32 v152, v164
	v_mov_b32_e32 v153, v165
	v_xor_b32_e32 v133, 0xe0, v129
	v_xor_b32_e32 v134, 0xf0, v129
	v_add3_u32 v130, v173, v133, v160
	v_add3_u32 v131, v173, v134, v160
	v_mfma_f32_32x32x16_bf16 v[48:63], v[174:177], v[100:103], v[48:63]
	v_mov_b32_e32 v164, v156
	v_mov_b32_e32 v165, v157
	v_mfma_f32_32x32x16_bf16 v[16:31], v[150:153], v[100:103], v[16:31]
	ds_read2st64_b64 v[150:153], v130 offset1:32
	ds_read2st64_b64 v[154:157], v131 offset1:32
	ds_read2st64_b64 v[174:177], v130 offset0:64 offset1:96
	ds_read2st64_b64 v[178:181], v131 offset0:64 offset1:96
	v_mfma_f32_32x32x16_bf16 v[0:15], v[164:167], v[100:103], v[0:15]
	s_waitcnt lgkmcnt(3)
	v_mov_b32_e32 v164, v150
	v_mov_b32_e32 v165, v151
	s_waitcnt lgkmcnt(2)
	v_mov_b32_e32 v166, v154
	v_mov_b32_e32 v167, v155
	v_mov_b32_e32 v154, v152
	v_mov_b32_e32 v155, v153
	s_waitcnt lgkmcnt(1)
	v_mov_b32_e32 v150, v174
	v_mov_b32_e32 v151, v175
	s_waitcnt lgkmcnt(0)
	v_mov_b32_e32 v152, v178
	v_mov_b32_e32 v153, v179
	v_add3_u32 v132, v173, v129, v160
	v_mfma_f32_32x32x16_bf16 v[48:63], v[164:167], v[96:99], v[48:63]
	v_add_u32_e32 v164, 0x100, v132
	v_xor_b32_e32 v132, 16, v129
	v_mov_b32_e32 v178, v176
	v_mov_b32_e32 v179, v177
	v_mfma_f32_32x32x16_bf16 v[16:31], v[150:153], v[96:99], v[16:31]
	v_add3_u32 v150, v173, v132, v160
	v_add_u32_e32 v173, 0x100, v150
	v_mfma_f32_32x32x16_bf16 v[32:47], v[154:157], v[96:99], v[32:47]
	ds_read2st64_b64 v[154:157], v164 offset1:32
	ds_read2st64_b64 v[150:153], v173 offset1:32
	ds_read2st64_b64 v[164:167], v164 offset0:64 offset1:96
	ds_read2st64_b64 v[174:177], v173 offset0:64 offset1:96
	v_mfma_f32_32x32x16_bf16 v[0:15], v[178:181], v[96:99], v[0:15]
	s_waitcnt lgkmcnt(2)
	v_mov_b32_e32 v180, v150
	v_mov_b32_e32 v181, v151
	v_mov_b32_e32 v150, v156
	v_mov_b32_e32 v151, v157
	v_mov_b32_e32 v178, v154
	v_mov_b32_e32 v179, v155
	v_mfma_f32_32x32x16_bf16 v[32:47], v[150:153], v[92:95], v[32:47]
	s_waitcnt lgkmcnt(1)
	v_mov_b32_e32 v150, v164
	v_mov_b32_e32 v151, v165
	s_waitcnt lgkmcnt(0)
	v_mov_b32_e32 v152, v174
	v_mov_b32_e32 v153, v175
	v_add_u32_e32 v149, 0x100, v149
	v_add_u32_e32 v158, 0x100, v158
	v_mov_b32_e32 v174, v166
	v_mfma_f32_32x32x16_bf16 v[48:63], v[178:181], v[92:95], v[48:63]
	v_mov_b32_e32 v175, v167
	v_mfma_f32_32x32x16_bf16 v[16:31], v[150:153], v[92:95], v[16:31]
	ds_read2st64_b64 v[150:153], v149 offset1:32
	ds_read2st64_b64 v[154:157], v158 offset1:32
	ds_read2st64_b64 v[164:167], v149 offset0:64 offset1:96
	ds_read2st64_b64 v[178:181], v158 offset0:64 offset1:96
	v_mfma_f32_32x32x16_bf16 v[0:15], v[174:177], v[92:95], v[0:15]
	s_waitcnt lgkmcnt(3)
; #define LAS __attribute__((address_space(3)))
; DI void attn_prompt_item(const Params& p, int item, ldsp lds, int tid_) {
;     ...
;     {
;       u32x2 va[4][2], vb[4][2];
;     ...
; #pragma unroll
;       for (int dt = 0; dt < 4; ++dt) { va[dt][0] = *(const LAS u32x2*)VF_ADDR(0, dt, 0); va[dt][1] = *(const LAS u32x2*)VF_ADDR(0, dt, 1); }
; #pragma unroll
;       for (int gi = 0; gi < 16; ++gi) {
;         if (gi + 1 < 16) {
; #pragma unroll
;           for (int dt = 0; dt < 4; ++dt) {
;             if (gi & 1) { va[dt][0] = *(const LAS u32x2*)VF_ADDR(gi + 1, dt, 0); va[dt][1] = *(const LAS u32x2*)VF_ADDR(gi + 1, dt, 1); }
;             else { vb[dt][0] = *(const LAS u32x2*)VF_ADDR(gi + 1, dt, 0); vb[dt][1] = *(const LAS u32x2*)VF_ADDR(gi + 1, dt, 1); } } }
; #pragma unroll
;         for (int dt = 0; dt < 4; ++dt) { const u32x2 lo = (gi & 1) ? vb[dt][0] : va[dt][0], hi = (gi & 1) ? vb[dt][1] : va[dt][1];
;           u32x4 vw; vw.x = lo.x; vw.y = lo.y; vw.z = hi.x; vw.w = hi.y;
;           O[dt] = __builtin_amdgcn_mfma_f32_32x32x16_bf16(__builtin_bit_cast(bf16x8, vw), pb[gi >> 1][gi & 1], O[dt], 0, 0, 0); }
;         __builtin_amdgcn_sched_barrier(0);
;       }
	v_mov_b32_e32 v174, v150
	v_mov_b32_e32 v175, v151
	s_waitcnt lgkmcnt(2)
	v_mov_b32_e32 v176, v154
	v_mov_b32_e32 v177, v155
	v_mov_b32_e32 v154, v152
	v_mov_b32_e32 v155, v153
	s_waitcnt lgkmcnt(1)
	v_mov_b32_e32 v150, v164
	v_mov_b32_e32 v151, v165
	s_waitcnt lgkmcnt(0)
	v_mov_b32_e32 v152, v178
	v_mov_b32_e32 v153, v179
	v_add_u32_e32 v149, 0x100, v159
	v_add_u32_e32 v158, 0x100, v182
	v_mfma_f32_32x32x16_bf16 v[48:63], v[174:177], v[88:91], v[48:63]
	v_mov_b32_e32 v178, v166
	v_mov_b32_e32 v179, v167
	v_mfma_f32_32x32x16_bf16 v[32:47], v[154:157], v[88:91], v[32:47]
	v_mfma_f32_32x32x16_bf16 v[16:31], v[150:153], v[88:91], v[16:31]
	ds_read2st64_b64 v[150:153], v149 offset1:32
	ds_read2st64_b64 v[154:157], v158 offset1:32
	ds_read2st64_b64 v[164:167], v149 offset0:64 offset1:96
	ds_read2st64_b64 v[174:177], v158 offset0:64 offset1:96
	v_mfma_f32_32x32x16_bf16 v[0:15], v[178:181], v[88:91], v[0:15]
	s_waitcnt lgkmcnt(3)
	v_mov_b32_e32 v178, v150
	v_mov_b32_e32 v179, v151
	s_waitcnt lgkmcnt(2)
	v_mov_b32_e32 v180, v154
	v_mov_b32_e32 v181, v155
	v_mov_b32_e32 v154, v152
	v_mov_b32_e32 v155, v153
	s_waitcnt lgkmcnt(1)
	v_mov_b32_e32 v150, v164
	v_mov_b32_e32 v151, v165
	s_waitcnt lgkmcnt(0)
	v_mov_b32_e32 v152, v174
	v_mov_b32_e32 v153, v175
	v_add_u32_e32 v149, 0x100, v183
	v_add_u32_e32 v158, 0x100, v184
	v_mfma_f32_32x32x16_bf16 v[48:63], v[178:181], v[84:87], v[48:63]
	v_mov_b32_e32 v174, v166
	v_mov_b32_e32 v175, v167
	v_mfma_f32_32x32x16_bf16 v[32:47], v[154:157], v[84:87], v[32:47]
	v_mfma_f32_32x32x16_bf16 v[16:31], v[150:153], v[84:87], v[16:31]
	ds_read2st64_b64 v[150:153], v149 offset1:32
	ds_read2st64_b64 v[154:157], v158 offset1:32
	ds_read2st64_b64 v[164:167], v149 offset0:64 offset1:96
	ds_read2st64_b64 v[178:181], v158 offset0:64 offset1:96
	v_mfma_f32_32x32x16_bf16 v[0:15], v[174:177], v[84:87], v[0:15]
	s_waitcnt lgkmcnt(3)
	v_mov_b32_e32 v174, v150
	v_mov_b32_e32 v175, v151
	s_waitcnt lgkmcnt(2)
	v_mov_b32_e32 v176, v154
	v_mov_b32_e32 v177, v155
	v_mov_b32_e32 v154, v152
	v_mov_b32_e32 v155, v153
	s_waitcnt lgkmcnt(1)
	v_mov_b32_e32 v150, v164
	v_mov_b32_e32 v151, v165
	s_waitcnt lgkmcnt(0)
	v_mov_b32_e32 v152, v178
	v_mov_b32_e32 v153, v179
	v_add_u32_e32 v149, 0x100, v185
	v_add_u32_e32 v158, 0x100, v186
	v_mfma_f32_32x32x16_bf16 v[48:63], v[174:177], v[80:83], v[48:63]
	v_mov_b32_e32 v178, v166
	v_mov_b32_e32 v179, v167
	v_mfma_f32_32x32x16_bf16 v[32:47], v[154:157], v[80:83], v[32:47]
	v_mfma_f32_32x32x16_bf16 v[16:31], v[150:153], v[80:83], v[16:31]
	ds_read2st64_b64 v[150:153], v149 offset1:32
	ds_read2st64_b64 v[154:157], v158 offset1:32
	ds_read2st64_b64 v[164:167], v149 offset0:64 offset1:96
	ds_read2st64_b64 v[174:177], v158 offset0:64 offset1:96
	v_mfma_f32_32x32x16_bf16 v[0:15], v[178:181], v[80:83], v[0:15]
	s_waitcnt lgkmcnt(3)
	v_mov_b32_e32 v178, v150
	v_mov_b32_e32 v179, v151
	s_waitcnt lgkmcnt(2)
	v_mov_b32_e32 v180, v154
	v_mov_b32_e32 v181, v155
	v_mov_b32_e32 v154, v152
	v_mov_b32_e32 v155, v153
	s_waitcnt lgkmcnt(1)
	v_mov_b32_e32 v150, v164
	v_mov_b32_e32 v151, v165
	s_waitcnt lgkmcnt(0)
	v_mov_b32_e32 v152, v174
	v_mov_b32_e32 v153, v175
	v_add_u32_e32 v149, 0x100, v187
	v_add_u32_e32 v158, 0x100, v188
	v_mfma_f32_32x32x16_bf16 v[48:63], v[178:181], v[76:79], v[48:63]
	v_mov_b32_e32 v174, v166
	v_mov_b32_e32 v175, v167
	v_mfma_f32_32x32x16_bf16 v[32:47], v[154:157], v[76:79], v[32:47]
	v_mfma_f32_32x32x16_bf16 v[16:31], v[150:153], v[76:79], v[16:31]
	ds_read2st64_b64 v[150:153], v149 offset1:32
	ds_read2st64_b64 v[154:157], v158 offset1:32
	ds_read2st64_b64 v[164:167], v149 offset0:64 offset1:96
	ds_read2st64_b64 v[178:181], v158 offset0:64 offset1:96
	v_mfma_f32_32x32x16_bf16 v[0:15], v[174:177], v[76:79], v[0:15]
	s_waitcnt lgkmcnt(3)
	v_mov_b32_e32 v174, v150
	v_mov_b32_e32 v175, v151
	s_waitcnt lgkmcnt(2)
	v_mov_b32_e32 v176, v154
	v_mov_b32_e32 v177, v155
	v_mov_b32_e32 v154, v152
	v_mov_b32_e32 v155, v153
	s_waitcnt lgkmcnt(1)
	v_mov_b32_e32 v150, v164
	v_mov_b32_e32 v151, v165
	s_waitcnt lgkmcnt(0)
	v_mov_b32_e32 v152, v178
	v_mov_b32_e32 v153, v179
	v_add_u32_e32 v149, 0x100, v189
	v_add_u32_e32 v158, 0x100, v190
	v_mfma_f32_32x32x16_bf16 v[48:63], v[174:177], v[72:75], v[48:63]
	v_mov_b32_e32 v178, v166
	v_mov_b32_e32 v179, v167
	v_mfma_f32_32x32x16_bf16 v[32:47], v[154:157], v[72:75], v[32:47]
	v_mfma_f32_32x32x16_bf16 v[16:31], v[150:153], v[72:75], v[16:31]
	ds_read2st64_b64 v[150:153], v149 offset1:32
	ds_read2st64_b64 v[154:157], v158 offset1:32
	ds_read2st64_b64 v[164:167], v149 offset0:64 offset1:96
	ds_read2st64_b64 v[174:177], v158 offset0:64 offset1:96
	v_mfma_f32_32x32x16_bf16 v[0:15], v[178:181], v[72:75], v[0:15]
	s_waitcnt lgkmcnt(3)
	v_mov_b32_e32 v178, v150
	v_mov_b32_e32 v179, v151
	s_waitcnt lgkmcnt(2)
	v_mov_b32_e32 v180, v154
	v_mov_b32_e32 v181, v155
	v_mov_b32_e32 v154, v152
	v_mov_b32_e32 v155, v153
	s_waitcnt lgkmcnt(1)
	v_mov_b32_e32 v150, v164
	v_mov_b32_e32 v151, v165
	s_waitcnt lgkmcnt(0)
	v_mov_b32_e32 v152, v174
	v_mov_b32_e32 v153, v175
	v_add_u32_e32 v130, 0x100, v130
	v_add_u32_e32 v131, 0x100, v131
	v_mfma_f32_32x32x16_bf16 v[48:63], v[178:181], v[68:71], v[48:63]
	v_mov_b32_e32 v174, v166
	v_mov_b32_e32 v175, v167
	v_mfma_f32_32x32x16_bf16 v[32:47], v[154:157], v[68:71], v[32:47]
	v_mfma_f32_32x32x16_bf16 v[16:31], v[150:153], v[68:71], v[16:31]
	ds_read2st64_b64 v[150:153], v130 offset1:32
	ds_read2st64_b64 v[154:157], v131 offset1:32
	ds_read2st64_b64 v[164:167], v130 offset0:64 offset1:96
	ds_read2st64_b64 v[178:181], v131 offset0:64 offset1:96
	v_mfma_f32_32x32x16_bf16 v[0:15], v[174:177], v[68:71], v[0:15]
	s_waitcnt lgkmcnt(3)
; DI unsigned pk2(float lo, float hi) { f32x2 v = {lo, hi}; return __builtin_bit_cast(unsigned, __builtin_convertvector(v, bf16x2v)); }
; DI void attn_prompt_item(const Params& p, int item, ldsp lds, int tid_) {
;     ...
;         for (int dt = 0; dt < 4; ++dt) { const u32x2 lo = (gi & 1) ? vb[dt][0] : va[dt][0], hi = (gi & 1) ? vb[dt][1] : va[dt][1];
;           u32x4 vw; vw.x = lo.x; vw.y = lo.y; vw.z = hi.x; vw.w = hi.y;
;           O[dt] = __builtin_amdgcn_mfma_f32_32x32x16_bf16(__builtin_bit_cast(bf16x8, vw), pb[gi >> 1][gi & 1], O[dt], 0, 0, 0); }
;         __builtin_amdgcn_sched_barrier(0);
;       }
;     ...
;     }
; #pragma unroll
;     for (int dt = 0; dt < 4; ++dt)
; #pragma unroll
;       for (int g4 = 0; g4 < 4; ++g4) { u32x2 w; w.x = pk2(O[dt][4 * g4] * inv, O[dt][4 * g4 + 1] * inv); w.y = pk2(O[dt][4 * g4 + 2] * inv, O[dt][4 * g4 + 3] * inv);
;         *(u32x2*)((bf16_t*)(p.ws + B_XA) + qrow * D + h * 256 + (dh * 4 + dt) * 32 + 8 * g4 + 4 * h2) = w; }
	v_mov_b32_e32 v174, v150
	v_mov_b32_e32 v175, v151
	s_waitcnt lgkmcnt(2)
	v_mov_b32_e32 v176, v154
	v_mov_b32_e32 v177, v155
	v_mov_b32_e32 v154, v152
	v_mov_b32_e32 v155, v153
	s_waitcnt lgkmcnt(1)
	v_mov_b32_e32 v150, v164
	v_mov_b32_e32 v151, v165
	s_waitcnt lgkmcnt(0)
	v_mov_b32_e32 v152, v178
	v_mov_b32_e32 v153, v179
	v_mov_b32_e32 v178, v166
	v_mov_b32_e32 v179, v167
	v_mfma_f32_32x32x16_bf16 v[48:63], v[174:177], v[64:67], v[48:63]
	v_mfma_f32_32x32x16_bf16 v[32:47], v[154:157], v[64:67], v[32:47]
	v_mfma_f32_32x32x16_bf16 v[16:31], v[150:153], v[64:67], v[16:31]
	v_mfma_f32_32x32x16_bf16 v[0:15], v[178:181], v[64:67], v[0:15]
	s_nop 8
	v_lshl_add_u64 v[196:197], s[42:43], 0, v[162:163]
	v_lshl_add_u64 v[196:197], v[196:197], 0, s[26:27]
	v_lshl_add_u64 v[196:197], v[196:197], 0, v[160:161]
	v_add_co_u32_e32 v130, vcc, s38, v196
	v_mbcnt_lo_u32_b32 v198, -1, 0
	v_mbcnt_hi_u32_b32 v198, -1, v198
	v_addc_co_u32_e32 v131, vcc, 0, v197, vcc
	v_and_b32_e32 v198, 32, v198
	v_lshrrev_b32_e32 v198, 2, v198
	v_mov_b32_e32 v199, 0
	v_lshl_add_u64 v[130:131], v[130:131], 0, v[198:199]
	v_pk_mul_f32 v[48:49], v[128:129], v[48:49] op_sel_hi:[0,1]
	v_pk_mul_f32 v[50:51], v[128:129], v[50:51] op_sel_hi:[0,1]
	v_pk_mul_f32 v[52:53], v[128:129], v[52:53] op_sel_hi:[0,1]
	v_pk_mul_f32 v[54:55], v[128:129], v[54:55] op_sel_hi:[0,1]
	v_cvt_pk_bf16_f32 v48, v48, v49
	v_cvt_pk_bf16_f32 v49, v50, v51
	v_cvt_pk_bf16_f32 v50, v52, v53
	v_cvt_pk_bf16_f32 v51, v54, v55
	v_pk_mul_f32 v[32:33], v[128:129], v[32:33] op_sel_hi:[0,1]
	v_pk_mul_f32 v[34:35], v[128:129], v[34:35] op_sel_hi:[0,1]
	v_pk_mul_f32 v[36:37], v[128:129], v[36:37] op_sel_hi:[0,1]
	v_pk_mul_f32 v[38:39], v[128:129], v[38:39] op_sel_hi:[0,1]
	v_cvt_pk_bf16_f32 v32, v32, v33
	v_cvt_pk_bf16_f32 v33, v34, v35
	v_cvt_pk_bf16_f32 v34, v36, v37
	v_cvt_pk_bf16_f32 v35, v38, v39
	v_pk_mul_f32 v[16:17], v[128:129], v[16:17] op_sel_hi:[0,1]
	v_pk_mul_f32 v[18:19], v[128:129], v[18:19] op_sel_hi:[0,1]
	v_pk_mul_f32 v[20:21], v[128:129], v[20:21] op_sel_hi:[0,1]
	v_pk_mul_f32 v[22:23], v[128:129], v[22:23] op_sel_hi:[0,1]
	v_cvt_pk_bf16_f32 v16, v16, v17
	v_cvt_pk_bf16_f32 v17, v18, v19
	v_cvt_pk_bf16_f32 v18, v20, v21
	v_cvt_pk_bf16_f32 v19, v22, v23
	v_pk_mul_f32 v[0:1], v[128:129], v[0:1] op_sel_hi:[0,1]
	v_pk_mul_f32 v[2:3], v[128:129], v[2:3] op_sel_hi:[0,1]
	v_pk_mul_f32 v[4:5], v[128:129], v[4:5] op_sel_hi:[0,1]
	v_pk_mul_f32 v[6:7], v[128:129], v[6:7] op_sel_hi:[0,1]
	v_cvt_pk_bf16_f32 v0, v0, v1
	v_cvt_pk_bf16_f32 v1, v2, v3
	v_cvt_pk_bf16_f32 v2, v4, v5
	v_cvt_pk_bf16_f32 v3, v6, v7
	s_nop 1
	v_permlane32_swap_b32_e32 v48, v50
	v_permlane32_swap_b32_e32 v49, v51
	global_store_dwordx4 v[130:131], v[48:51], off
	v_permlane32_swap_b32_e32 v32, v34
	v_permlane32_swap_b32_e32 v33, v35
	global_store_dwordx4 v[130:131], v[32:35], off offset:64
	v_permlane32_swap_b32_e32 v16, v18
	v_permlane32_swap_b32_e32 v17, v19
	global_store_dwordx4 v[130:131], v[16:19], off offset:128
	v_permlane32_swap_b32_e32 v0, v2
	v_permlane32_swap_b32_e32 v1, v3
	global_store_dwordx4 v[130:131], v[0:3], off offset:192
	v_pk_mul_f32 v[56:57], v[128:129], v[56:57] op_sel_hi:[0,1]
	v_pk_mul_f32 v[58:59], v[128:129], v[58:59] op_sel_hi:[0,1]
	v_pk_mul_f32 v[60:61], v[128:129], v[60:61] op_sel_hi:[0,1]
	v_pk_mul_f32 v[62:63], v[128:129], v[62:63] op_sel_hi:[0,1]
	v_cvt_pk_bf16_f32 v56, v56, v57
	v_cvt_pk_bf16_f32 v57, v58, v59
	v_cvt_pk_bf16_f32 v58, v60, v61
	v_cvt_pk_bf16_f32 v59, v62, v63
	v_pk_mul_f32 v[40:41], v[128:129], v[40:41] op_sel_hi:[0,1]
	v_pk_mul_f32 v[42:43], v[128:129], v[42:43] op_sel_hi:[0,1]
	v_pk_mul_f32 v[44:45], v[128:129], v[44:45] op_sel_hi:[0,1]
	v_pk_mul_f32 v[46:47], v[128:129], v[46:47] op_sel_hi:[0,1]
	v_cvt_pk_bf16_f32 v40, v40, v41
	v_cvt_pk_bf16_f32 v41, v42, v43
	v_cvt_pk_bf16_f32 v42, v44, v45
	v_cvt_pk_bf16_f32 v43, v46, v47
	v_pk_mul_f32 v[24:25], v[128:129], v[24:25] op_sel_hi:[0,1]
	v_pk_mul_f32 v[26:27], v[128:129], v[26:27] op_sel_hi:[0,1]
	v_pk_mul_f32 v[28:29], v[128:129], v[28:29] op_sel_hi:[0,1]
	v_pk_mul_f32 v[30:31], v[128:129], v[30:31] op_sel_hi:[0,1]
	v_cvt_pk_bf16_f32 v24, v24, v25
	v_cvt_pk_bf16_f32 v25, v26, v27
	v_cvt_pk_bf16_f32 v26, v28, v29
	v_cvt_pk_bf16_f32 v27, v30, v31
	v_pk_mul_f32 v[8:9], v[128:129], v[8:9] op_sel_hi:[0,1]
	v_pk_mul_f32 v[10:11], v[128:129], v[10:11] op_sel_hi:[0,1]
	v_pk_mul_f32 v[12:13], v[128:129], v[12:13] op_sel_hi:[0,1]
	v_pk_mul_f32 v[14:15], v[128:129], v[14:15] op_sel_hi:[0,1]
	v_cvt_pk_bf16_f32 v8, v8, v9
	v_cvt_pk_bf16_f32 v9, v10, v11
	v_cvt_pk_bf16_f32 v10, v12, v13
	v_cvt_pk_bf16_f32 v11, v14, v15
	s_nop 1
	v_permlane32_swap_b32_e32 v56, v58
	v_permlane32_swap_b32_e32 v57, v59
	global_store_dwordx4 v[130:131], v[56:59], off offset:32
	v_permlane32_swap_b32_e32 v40, v42
	v_permlane32_swap_b32_e32 v41, v43
	global_store_dwordx4 v[130:131], v[40:43], off offset:96
	v_permlane32_swap_b32_e32 v24, v26
	v_permlane32_swap_b32_e32 v25, v27
	global_store_dwordx4 v[130:131], v[24:27], off offset:160
	v_permlane32_swap_b32_e32 v8, v10
	v_permlane32_swap_b32_e32 v9, v11
	global_store_dwordx4 v[130:131], v[8:11], off offset:224
	v_add_u32_e32 v158, s39, v172
	v_add3_u32 v0, v158, v146, v160
	v_add3_u32 v2, v158, v139, v160
	ds_read_b64 v[0:1], v0
	ds_read_b64 v[2:3], v2
	v_add_u32_e32 v159, s40, v172
	v_add_u32_e32 v166, s41, v172
	v_add_u32_e32 v167, s44, v172
	v_add3_u32 v4, v159, v146, v160
	v_add3_u32 v6, v159, v139, v160
	v_add3_u32 v8, v166, v146, v160
	v_add3_u32 v9, v166, v139, v160
	v_add3_u32 v10, v167, v146, v160
	v_add3_u32 v11, v167, v139, v160
	v_add3_u32 v139, v158, v147, v160
	v_add3_u32 v175, v166, v147, v160
	ds_read_b64 v[4:5], v4
	ds_read_b64 v[6:7], v6
	s_waitcnt lgkmcnt(2)
; #define LAS __attribute__((address_space(3)))
; DI void attn_prompt_item(const Params& p, int item, ldsp lds, int tid_) {
;     ...
;   for (int dh = 0; dh < 2; ++dh) {
;     f32x16 O[4];
; #pragma unroll
;     for (int dt = 0; dt < 4; ++dt)
; #pragma unroll
;       for (int i = 0; i < 16; ++i) O[dt][i] = 0.f;
;     {
;       u32x2 va[4][2], vb[4][2];
;     ...
; #pragma unroll
;       for (int dt = 0; dt < 4; ++dt) { va[dt][0] = *(const LAS u32x2*)VF_ADDR(0, dt, 0); va[dt][1] = *(const LAS u32x2*)VF_ADDR(0, dt, 1); }
; #pragma unroll
;       for (int gi = 0; gi < 16; ++gi) {
;         if (gi + 1 < 16) {
; #pragma unroll
;           for (int dt = 0; dt < 4; ++dt) {
;             if (gi & 1) { va[dt][0] = *(const LAS u32x2*)VF_ADDR(gi + 1, dt, 0); va[dt][1] = *(const LAS u32x2*)VF_ADDR(gi + 1, dt, 1); }
;             else { vb[dt][0] = *(const LAS u32x2*)VF_ADDR(gi + 1, dt, 0); vb[dt][1] = *(const LAS u32x2*)VF_ADDR(gi + 1, dt, 1); } } }
; #pragma unroll
;         for (int dt = 0; dt < 4; ++dt) { const u32x2 lo = (gi & 1) ? vb[dt][0] : va[dt][0], hi = (gi & 1) ? vb[dt][1] : va[dt][1];
;           u32x4 vw; vw.x = lo.x; vw.y = lo.y; vw.z = hi.x; vw.w = hi.y;
;           O[dt] = __builtin_amdgcn_mfma_f32_32x32x16_bf16(__builtin_bit_cast(bf16x8, vw), pb[gi >> 1][gi & 1], O[dt], 0, 0, 0); }
;         __builtin_amdgcn_sched_barrier(0);
;       }
	v_mfma_f32_32x32x16_bf16 v[48:63], v[0:3], v[108:111], 0
	ds_read_b64 v[0:1], v8
	ds_read_b64 v[2:3], v9
	ds_read_b64 v[8:9], v10
	ds_read_b64 v[10:11], v11
	v_add3_u32 v172, v158, v148, v160
	v_add3_u32 v173, v159, v147, v160
	v_add3_u32 v174, v159, v148, v160
	ds_read_b64 v[150:151], v139
	ds_read_b64 v[152:153], v172
	ds_read_b64 v[154:155], v173
	ds_read_b64 v[156:157], v174
	v_add3_u32 v176, v166, v148, v160
	v_add3_u32 v177, v167, v147, v160
	v_add3_u32 v178, v167, v148, v160
	ds_read_b64 v[146:147], v175
	ds_read_b64 v[148:149], v176
	ds_read_b64 v[162:163], v177
	ds_read_b64 v[164:165], v178
	s_waitcnt lgkmcnt(12)
	v_mfma_f32_32x32x16_bf16 v[32:47], v[4:7], v[108:111], 0
	s_waitcnt lgkmcnt(10)
	v_mfma_f32_32x32x16_bf16 v[16:31], v[0:3], v[108:111], 0
	s_waitcnt lgkmcnt(8)
	v_mfma_f32_32x32x16_bf16 v[0:15], v[8:11], v[108:111], 0
	v_add3_u32 v179, v158, v144, v160
	v_add3_u32 v183, v166, v144, v160
	s_waitcnt lgkmcnt(6)
	v_mfma_f32_32x32x16_bf16 v[48:63], v[150:153], v[124:127], v[48:63]
	v_add3_u32 v180, v158, v145, v160
	v_add3_u32 v181, v159, v144, v160
	v_add3_u32 v182, v159, v145, v160
	ds_read_b64 v[108:109], v179
	ds_read_b64 v[110:111], v180
	ds_read_b64 v[150:151], v181
	ds_read_b64 v[152:153], v182
	v_add3_u32 v184, v166, v145, v160
	v_add3_u32 v185, v167, v144, v160
	v_add3_u32 v186, v167, v145, v160
	s_waitcnt lgkmcnt(8)
	v_mfma_f32_32x32x16_bf16 v[32:47], v[154:157], v[124:127], v[32:47]
	s_waitcnt lgkmcnt(6)
	v_mfma_f32_32x32x16_bf16 v[16:31], v[146:149], v[124:127], v[16:31]
	ds_read_b64 v[144:145], v183
	ds_read_b64 v[146:147], v184
	ds_read_b64 v[154:155], v185
	ds_read_b64 v[156:157], v186
	s_waitcnt lgkmcnt(8)
	v_mfma_f32_32x32x16_bf16 v[0:15], v[162:165], v[124:127], v[0:15]
	v_add3_u32 v162, v158, v142, v160
	s_waitcnt lgkmcnt(4)
	v_mfma_f32_32x32x16_bf16 v[32:47], v[150:153], v[120:123], v[32:47]
	v_add3_u32 v152, v166, v142, v160
	v_add3_u32 v163, v158, v143, v160
	v_add3_u32 v150, v159, v142, v160
	v_add3_u32 v151, v159, v143, v160
	v_add3_u32 v153, v166, v143, v160
	v_add3_u32 v164, v167, v142, v160
	v_add3_u32 v165, v167, v143, v160
	v_mfma_f32_32x32x16_bf16 v[48:63], v[108:111], v[120:123], v[48:63]
	ds_read_b64 v[108:109], v162
	ds_read_b64 v[110:111], v163
	ds_read_b64 v[124:125], v150
	ds_read_b64 v[126:127], v151
	s_waitcnt lgkmcnt(6)
	v_mfma_f32_32x32x16_bf16 v[16:31], v[144:147], v[120:123], v[16:31]
	ds_read_b64 v[142:143], v152
	ds_read_b64 v[144:145], v153
	ds_read_b64 v[146:147], v164
	ds_read_b64 v[148:149], v165
	s_waitcnt lgkmcnt(8)
	v_mfma_f32_32x32x16_bf16 v[0:15], v[154:157], v[120:123], v[0:15]
	v_add3_u32 v154, v158, v140, v160
	v_add3_u32 v187, v166, v140, v160
	s_waitcnt lgkmcnt(6)
	v_mfma_f32_32x32x16_bf16 v[48:63], v[108:111], v[116:119], v[48:63]
	v_add3_u32 v155, v158, v141, v160
	v_add3_u32 v156, v159, v140, v160
	v_add3_u32 v157, v159, v141, v160
	ds_read_b64 v[108:109], v154
	ds_read_b64 v[110:111], v155
	ds_read_b64 v[120:121], v156
	ds_read_b64 v[122:123], v157
	v_add3_u32 v188, v167, v141, v160
	s_waitcnt lgkmcnt(8)
	v_mfma_f32_32x32x16_bf16 v[32:47], v[124:127], v[116:119], v[32:47]
	s_waitcnt lgkmcnt(6)
	v_mfma_f32_32x32x16_bf16 v[16:31], v[142:145], v[116:119], v[16:31]
	v_add3_u32 v144, v166, v141, v160
	v_add3_u32 v145, v167, v140, v160
	ds_read_b64 v[124:125], v187
	ds_read_b64 v[126:127], v144
	ds_read_b64 v[140:141], v145
	ds_read_b64 v[142:143], v188
	s_waitcnt lgkmcnt(8)
	v_mfma_f32_32x32x16_bf16 v[0:15], v[146:149], v[116:119], v[0:15]
	v_add3_u32 v146, v158, v137, v160
	v_add3_u32 v189, v166, v137, v160
	s_waitcnt lgkmcnt(6)
	v_mfma_f32_32x32x16_bf16 v[48:63], v[108:111], v[112:115], v[48:63]
	v_add3_u32 v147, v158, v138, v160
	v_add3_u32 v148, v159, v137, v160
	v_add3_u32 v149, v159, v138, v160
	ds_read_b64 v[108:109], v146
	ds_read_b64 v[110:111], v147
	ds_read_b64 v[116:117], v148
	ds_read_b64 v[118:119], v149
	v_add3_u32 v190, v166, v138, v160
	v_add3_u32 v137, v167, v137, v160
	v_add3_u32 v138, v167, v138, v160
	s_waitcnt lgkmcnt(8)
	v_mfma_f32_32x32x16_bf16 v[32:47], v[120:123], v[112:115], v[32:47]
	s_waitcnt lgkmcnt(6)
	v_mfma_f32_32x32x16_bf16 v[16:31], v[124:127], v[112:115], v[16:31]
	ds_read_b64 v[120:121], v189
	ds_read_b64 v[122:123], v190
	ds_read_b64 v[124:125], v137
	ds_read_b64 v[126:127], v138
	s_waitcnt lgkmcnt(8)
	v_mfma_f32_32x32x16_bf16 v[0:15], v[140:143], v[112:115], v[0:15]
	v_add3_u32 v140, v158, v135, v160
	v_add3_u32 v191, v166, v135, v160
	s_waitcnt lgkmcnt(6)
	v_mfma_f32_32x32x16_bf16 v[48:63], v[108:111], v[104:107], v[48:63]
	v_add3_u32 v141, v158, v136, v160
	v_add3_u32 v142, v159, v135, v160
	v_add3_u32 v143, v159, v136, v160
	ds_read_b64 v[108:109], v140
	ds_read_b64 v[110:111], v141
	ds_read_b64 v[112:113], v142
	ds_read_b64 v[114:115], v143
	v_add3_u32 v192, v166, v136, v160
	v_add3_u32 v135, v167, v135, v160
	v_add3_u32 v136, v167, v136, v160
	s_waitcnt lgkmcnt(8)
	v_mfma_f32_32x32x16_bf16 v[32:47], v[116:119], v[104:107], v[32:47]
	s_waitcnt lgkmcnt(6)
	v_mfma_f32_32x32x16_bf16 v[16:31], v[120:123], v[104:107], v[16:31]
	ds_read_b64 v[116:117], v191
	ds_read_b64 v[118:119], v192
	ds_read_b64 v[120:121], v135
	ds_read_b64 v[122:123], v136
	s_waitcnt lgkmcnt(8)
	v_mfma_f32_32x32x16_bf16 v[0:15], v[124:127], v[104:107], v[0:15]
	v_add3_u32 v124, v158, v133, v160
	v_add3_u32 v193, v166, v133, v160
	s_waitcnt lgkmcnt(6)
	v_mfma_f32_32x32x16_bf16 v[48:63], v[108:111], v[100:103], v[48:63]
	v_add3_u32 v125, v158, v134, v160
	v_add3_u32 v126, v159, v133, v160
	v_add3_u32 v127, v159, v134, v160
	ds_read_b64 v[104:105], v124
	ds_read_b64 v[106:107], v125
	ds_read_b64 v[108:109], v126
	ds_read_b64 v[110:111], v127
	v_add3_u32 v194, v166, v134, v160
	v_add3_u32 v133, v167, v133, v160
	v_add3_u32 v134, v167, v134, v160
	s_waitcnt lgkmcnt(8)
; #define LAS __attribute__((address_space(3)))
; DI void attn_prompt_item(const Params& p, int item, ldsp lds, int tid_) {
;     ...
;       for (int gi = 0; gi < 16; ++gi) {
;         if (gi + 1 < 16) {
; #pragma unroll
;           for (int dt = 0; dt < 4; ++dt) {
;             if (gi & 1) { va[dt][0] = *(const LAS u32x2*)VF_ADDR(gi + 1, dt, 0); va[dt][1] = *(const LAS u32x2*)VF_ADDR(gi + 1, dt, 1); }
;             else { vb[dt][0] = *(const LAS u32x2*)VF_ADDR(gi + 1, dt, 0); vb[dt][1] = *(const LAS u32x2*)VF_ADDR(gi + 1, dt, 1); } } }
; #pragma unroll
;         for (int dt = 0; dt < 4; ++dt) { const u32x2 lo = (gi & 1) ? vb[dt][0] : va[dt][0], hi = (gi & 1) ? vb[dt][1] : va[dt][1];
;           u32x4 vw; vw.x = lo.x; vw.y = lo.y; vw.z = hi.x; vw.w = hi.y;
;           O[dt] = __builtin_amdgcn_mfma_f32_32x32x16_bf16(__builtin_bit_cast(bf16x8, vw), pb[gi >> 1][gi & 1], O[dt], 0, 0, 0); }
;         __builtin_amdgcn_sched_barrier(0);
;       }
	v_mfma_f32_32x32x16_bf16 v[32:47], v[112:115], v[100:103], v[32:47]
	s_waitcnt lgkmcnt(6)
	v_mfma_f32_32x32x16_bf16 v[16:31], v[116:119], v[100:103], v[16:31]
	ds_read_b64 v[112:113], v193
	ds_read_b64 v[114:115], v194
	ds_read_b64 v[116:117], v133
	ds_read_b64 v[118:119], v134
	s_waitcnt lgkmcnt(8)
	v_mfma_f32_32x32x16_bf16 v[0:15], v[120:123], v[100:103], v[0:15]
	s_waitcnt lgkmcnt(6)
	v_mfma_f32_32x32x16_bf16 v[48:63], v[104:107], v[96:99], v[48:63]
	v_add3_u32 v100, v158, v129, v160
	v_add3_u32 v102, v158, v132, v160
	v_add3_u32 v104, v159, v129, v160
	v_add3_u32 v106, v159, v132, v160
	ds_read_b64 v[100:101], v100 offset:256
	ds_read_b64 v[102:103], v102 offset:256
	ds_read_b64 v[104:105], v104 offset:256
	ds_read_b64 v[106:107], v106 offset:256
	s_waitcnt lgkmcnt(8)
	v_mfma_f32_32x32x16_bf16 v[32:47], v[108:111], v[96:99], v[32:47]
	v_add3_u32 v108, v166, v129, v160
	v_add3_u32 v110, v166, v132, v160
	s_waitcnt lgkmcnt(6)
	v_mfma_f32_32x32x16_bf16 v[16:31], v[112:115], v[96:99], v[16:31]
	v_add3_u32 v112, v167, v129, v160
	v_add3_u32 v114, v167, v132, v160
	ds_read_b64 v[108:109], v108 offset:256
	ds_read_b64 v[110:111], v110 offset:256
	ds_read_b64 v[112:113], v112 offset:256
	ds_read_b64 v[114:115], v114 offset:256
	s_waitcnt lgkmcnt(8)
	v_mfma_f32_32x32x16_bf16 v[0:15], v[116:119], v[96:99], v[0:15]
	s_waitcnt lgkmcnt(6)
	v_mfma_f32_32x32x16_bf16 v[48:63], v[100:103], v[92:95], v[48:63]
	s_waitcnt lgkmcnt(4)
	v_mfma_f32_32x32x16_bf16 v[32:47], v[104:107], v[92:95], v[32:47]
	s_waitcnt lgkmcnt(2)
	v_mfma_f32_32x32x16_bf16 v[16:31], v[108:111], v[92:95], v[16:31]
	ds_read_b64 v[96:97], v139 offset:256
	ds_read_b64 v[98:99], v172 offset:256
	ds_read_b64 v[100:101], v173 offset:256
	ds_read_b64 v[102:103], v174 offset:256
	ds_read_b64 v[104:105], v175 offset:256
	ds_read_b64 v[106:107], v176 offset:256
	ds_read_b64 v[108:109], v177 offset:256
	ds_read_b64 v[110:111], v178 offset:256
	s_waitcnt lgkmcnt(8)
	v_mfma_f32_32x32x16_bf16 v[0:15], v[112:115], v[92:95], v[0:15]
	s_waitcnt lgkmcnt(6)
	v_mfma_f32_32x32x16_bf16 v[48:63], v[96:99], v[88:91], v[48:63]
	s_waitcnt lgkmcnt(4)
	v_mfma_f32_32x32x16_bf16 v[32:47], v[100:103], v[88:91], v[32:47]
	s_waitcnt lgkmcnt(2)
	v_mfma_f32_32x32x16_bf16 v[16:31], v[104:107], v[88:91], v[16:31]
	ds_read_b64 v[92:93], v179 offset:256
	ds_read_b64 v[94:95], v180 offset:256
	ds_read_b64 v[96:97], v181 offset:256
	ds_read_b64 v[98:99], v182 offset:256
	ds_read_b64 v[100:101], v183 offset:256
	ds_read_b64 v[102:103], v184 offset:256
	ds_read_b64 v[104:105], v185 offset:256
	ds_read_b64 v[106:107], v186 offset:256
	s_waitcnt lgkmcnt(8)
	v_mfma_f32_32x32x16_bf16 v[0:15], v[108:111], v[88:91], v[0:15]
	s_waitcnt lgkmcnt(6)
	v_mfma_f32_32x32x16_bf16 v[48:63], v[92:95], v[84:87], v[48:63]
	s_waitcnt lgkmcnt(4)
	v_mfma_f32_32x32x16_bf16 v[32:47], v[96:99], v[84:87], v[32:47]
	s_waitcnt lgkmcnt(2)
	v_mfma_f32_32x32x16_bf16 v[16:31], v[100:103], v[84:87], v[16:31]
	ds_read_b64 v[88:89], v162 offset:256
	ds_read_b64 v[90:91], v163 offset:256
	ds_read_b64 v[92:93], v150 offset:256
	ds_read_b64 v[94:95], v151 offset:256
	ds_read_b64 v[96:97], v152 offset:256
	ds_read_b64 v[98:99], v153 offset:256
	ds_read_b64 v[100:101], v164 offset:256
	ds_read_b64 v[102:103], v165 offset:256
	s_waitcnt lgkmcnt(8)
	v_mfma_f32_32x32x16_bf16 v[0:15], v[104:107], v[84:87], v[0:15]
	s_waitcnt lgkmcnt(6)
	v_mfma_f32_32x32x16_bf16 v[48:63], v[88:91], v[80:83], v[48:63]
	s_waitcnt lgkmcnt(4)
	v_mfma_f32_32x32x16_bf16 v[32:47], v[92:95], v[80:83], v[32:47]
	s_waitcnt lgkmcnt(2)
	v_mfma_f32_32x32x16_bf16 v[16:31], v[96:99], v[80:83], v[16:31]
	ds_read_b64 v[84:85], v154 offset:256
	ds_read_b64 v[86:87], v155 offset:256
	ds_read_b64 v[88:89], v156 offset:256
	ds_read_b64 v[90:91], v157 offset:256
	ds_read_b64 v[92:93], v187 offset:256
	ds_read_b64 v[94:95], v144 offset:256
	ds_read_b64 v[96:97], v145 offset:256
	ds_read_b64 v[98:99], v188 offset:256
	s_waitcnt lgkmcnt(8)
	v_mfma_f32_32x32x16_bf16 v[0:15], v[100:103], v[80:83], v[0:15]
	s_waitcnt lgkmcnt(6)
	v_mfma_f32_32x32x16_bf16 v[48:63], v[84:87], v[76:79], v[48:63]
	s_waitcnt lgkmcnt(4)
	v_mfma_f32_32x32x16_bf16 v[32:47], v[88:91], v[76:79], v[32:47]
	s_waitcnt lgkmcnt(2)
	v_mfma_f32_32x32x16_bf16 v[16:31], v[92:95], v[76:79], v[16:31]
	ds_read_b64 v[80:81], v146 offset:256
	ds_read_b64 v[82:83], v147 offset:256
	ds_read_b64 v[84:85], v148 offset:256
	ds_read_b64 v[86:87], v149 offset:256
	ds_read_b64 v[88:89], v189 offset:256
	ds_read_b64 v[90:91], v190 offset:256
	ds_read_b64 v[92:93], v137 offset:256
	ds_read_b64 v[94:95], v138 offset:256
	s_waitcnt lgkmcnt(8)
	v_mfma_f32_32x32x16_bf16 v[0:15], v[96:99], v[76:79], v[0:15]
	s_waitcnt lgkmcnt(6)
	v_mfma_f32_32x32x16_bf16 v[48:63], v[80:83], v[72:75], v[48:63]
	s_waitcnt lgkmcnt(4)
	v_mfma_f32_32x32x16_bf16 v[32:47], v[84:87], v[72:75], v[32:47]
	s_waitcnt lgkmcnt(2)
	v_mfma_f32_32x32x16_bf16 v[16:31], v[88:91], v[72:75], v[16:31]
	ds_read_b64 v[76:77], v140 offset:256
	ds_read_b64 v[78:79], v141 offset:256
	ds_read_b64 v[80:81], v142 offset:256
	ds_read_b64 v[82:83], v143 offset:256
	ds_read_b64 v[84:85], v191 offset:256
	ds_read_b64 v[86:87], v192 offset:256
	ds_read_b64 v[88:89], v135 offset:256
	ds_read_b64 v[90:91], v136 offset:256
	s_waitcnt lgkmcnt(8)
; DI unsigned pk2(float lo, float hi) { f32x2 v = {lo, hi}; return __builtin_bit_cast(unsigned, __builtin_convertvector(v, bf16x2v)); }
; DI void attn_prompt_item(const Params& p, int item, ldsp lds, int tid_) {
;     ...
;         for (int dt = 0; dt < 4; ++dt) { const u32x2 lo = (gi & 1) ? vb[dt][0] : va[dt][0], hi = (gi & 1) ? vb[dt][1] : va[dt][1];
;           u32x4 vw; vw.x = lo.x; vw.y = lo.y; vw.z = hi.x; vw.w = hi.y;
;           O[dt] = __builtin_amdgcn_mfma_f32_32x32x16_bf16(__builtin_bit_cast(bf16x8, vw), pb[gi >> 1][gi & 1], O[dt], 0, 0, 0); }
;         __builtin_amdgcn_sched_barrier(0);
;       }
;     ...
;     }
; #pragma unroll
;     for (int dt = 0; dt < 4; ++dt)
; #pragma unroll
;       for (int g4 = 0; g4 < 4; ++g4) { u32x2 w; w.x = pk2(O[dt][4 * g4] * inv, O[dt][4 * g4 + 1] * inv); w.y = pk2(O[dt][4 * g4 + 2] * inv, O[dt][4 * g4 + 3] * inv);
;         *(u32x2*)((bf16_t*)(p.ws + B_XA) + qrow * D + h * 256 + (dh * 4 + dt) * 32 + 8 * g4 + 4 * h2) = w; }
;   }
	v_mfma_f32_32x32x16_bf16 v[0:15], v[92:95], v[72:75], v[0:15]
	s_waitcnt lgkmcnt(6)
	v_mfma_f32_32x32x16_bf16 v[48:63], v[76:79], v[68:71], v[48:63]
	s_waitcnt lgkmcnt(4)
	v_mfma_f32_32x32x16_bf16 v[32:47], v[80:83], v[68:71], v[32:47]
	s_waitcnt lgkmcnt(2)
	v_mfma_f32_32x32x16_bf16 v[16:31], v[84:87], v[68:71], v[16:31]
	ds_read_b64 v[72:73], v124 offset:256
	ds_read_b64 v[74:75], v125 offset:256
	ds_read_b64 v[76:77], v126 offset:256
	ds_read_b64 v[78:79], v127 offset:256
	ds_read_b64 v[80:81], v193 offset:256
	ds_read_b64 v[82:83], v194 offset:256
	ds_read_b64 v[84:85], v133 offset:256
	ds_read_b64 v[86:87], v134 offset:256
	s_waitcnt lgkmcnt(8)
	v_mfma_f32_32x32x16_bf16 v[0:15], v[88:91], v[68:71], v[0:15]
	s_waitcnt lgkmcnt(6)
	v_mfma_f32_32x32x16_bf16 v[48:63], v[72:75], v[64:67], v[48:63]
	s_waitcnt lgkmcnt(4)
	v_mfma_f32_32x32x16_bf16 v[32:47], v[76:79], v[64:67], v[32:47]
	s_waitcnt lgkmcnt(2)
	v_mfma_f32_32x32x16_bf16 v[16:31], v[80:83], v[64:67], v[16:31]
	s_waitcnt lgkmcnt(0)
	v_mfma_f32_32x32x16_bf16 v[0:15], v[84:87], v[64:67], v[0:15]
	s_nop 5
	v_pk_mul_f32 v[48:49], v[128:129], v[48:49] op_sel_hi:[0,1]
	v_pk_mul_f32 v[50:51], v[128:129], v[50:51] op_sel_hi:[0,1]
	v_pk_mul_f32 v[52:53], v[128:129], v[52:53] op_sel_hi:[0,1]
	v_pk_mul_f32 v[54:55], v[128:129], v[54:55] op_sel_hi:[0,1]
	v_cvt_pk_bf16_f32 v48, v48, v49
	v_cvt_pk_bf16_f32 v49, v50, v51
	v_cvt_pk_bf16_f32 v50, v52, v53
	v_cvt_pk_bf16_f32 v51, v54, v55
	v_pk_mul_f32 v[32:33], v[128:129], v[32:33] op_sel_hi:[0,1]
	v_pk_mul_f32 v[34:35], v[128:129], v[34:35] op_sel_hi:[0,1]
	v_pk_mul_f32 v[36:37], v[128:129], v[36:37] op_sel_hi:[0,1]
	v_pk_mul_f32 v[38:39], v[128:129], v[38:39] op_sel_hi:[0,1]
	v_cvt_pk_bf16_f32 v32, v32, v33
	v_cvt_pk_bf16_f32 v33, v34, v35
	v_cvt_pk_bf16_f32 v34, v36, v37
	v_cvt_pk_bf16_f32 v35, v38, v39
	v_pk_mul_f32 v[16:17], v[128:129], v[16:17] op_sel_hi:[0,1]
	v_pk_mul_f32 v[18:19], v[128:129], v[18:19] op_sel_hi:[0,1]
	v_pk_mul_f32 v[20:21], v[128:129], v[20:21] op_sel_hi:[0,1]
	v_pk_mul_f32 v[22:23], v[128:129], v[22:23] op_sel_hi:[0,1]
	v_cvt_pk_bf16_f32 v16, v16, v17
	v_cvt_pk_bf16_f32 v17, v18, v19
	v_cvt_pk_bf16_f32 v18, v20, v21
	v_cvt_pk_bf16_f32 v19, v22, v23
	v_pk_mul_f32 v[0:1], v[128:129], v[0:1] op_sel_hi:[0,1]
	v_pk_mul_f32 v[2:3], v[128:129], v[2:3] op_sel_hi:[0,1]
	v_pk_mul_f32 v[4:5], v[128:129], v[4:5] op_sel_hi:[0,1]
	v_pk_mul_f32 v[6:7], v[128:129], v[6:7] op_sel_hi:[0,1]
	v_cvt_pk_bf16_f32 v0, v0, v1
	v_cvt_pk_bf16_f32 v1, v2, v3
	v_cvt_pk_bf16_f32 v2, v4, v5
	v_cvt_pk_bf16_f32 v3, v6, v7
	s_nop 1
	v_permlane32_swap_b32_e32 v48, v50
	v_permlane32_swap_b32_e32 v49, v51
	global_store_dwordx4 v[130:131], v[48:51], off offset:256
	v_permlane32_swap_b32_e32 v32, v34
	v_permlane32_swap_b32_e32 v33, v35
	global_store_dwordx4 v[130:131], v[32:35], off offset:320
	v_permlane32_swap_b32_e32 v16, v18
	v_permlane32_swap_b32_e32 v17, v19
	global_store_dwordx4 v[130:131], v[16:19], off offset:384
	v_permlane32_swap_b32_e32 v0, v2
	v_permlane32_swap_b32_e32 v1, v3
	global_store_dwordx4 v[130:131], v[0:3], off offset:448
	v_pk_mul_f32 v[56:57], v[128:129], v[56:57] op_sel_hi:[0,1]
	v_pk_mul_f32 v[58:59], v[128:129], v[58:59] op_sel_hi:[0,1]
	v_pk_mul_f32 v[60:61], v[128:129], v[60:61] op_sel_hi:[0,1]
	v_pk_mul_f32 v[62:63], v[128:129], v[62:63] op_sel_hi:[0,1]
	v_cvt_pk_bf16_f32 v56, v56, v57
	v_cvt_pk_bf16_f32 v57, v58, v59
	v_cvt_pk_bf16_f32 v58, v60, v61
	v_cvt_pk_bf16_f32 v59, v62, v63
	v_pk_mul_f32 v[40:41], v[128:129], v[40:41] op_sel_hi:[0,1]
	v_pk_mul_f32 v[42:43], v[128:129], v[42:43] op_sel_hi:[0,1]
	v_pk_mul_f32 v[44:45], v[128:129], v[44:45] op_sel_hi:[0,1]
	v_pk_mul_f32 v[46:47], v[128:129], v[46:47] op_sel_hi:[0,1]
	v_cvt_pk_bf16_f32 v40, v40, v41
	v_cvt_pk_bf16_f32 v41, v42, v43
	v_cvt_pk_bf16_f32 v42, v44, v45
	v_cvt_pk_bf16_f32 v43, v46, v47
	v_pk_mul_f32 v[24:25], v[128:129], v[24:25] op_sel_hi:[0,1]
	v_pk_mul_f32 v[26:27], v[128:129], v[26:27] op_sel_hi:[0,1]
	v_pk_mul_f32 v[28:29], v[128:129], v[28:29] op_sel_hi:[0,1]
	v_pk_mul_f32 v[30:31], v[128:129], v[30:31] op_sel_hi:[0,1]
	v_cvt_pk_bf16_f32 v24, v24, v25
	v_cvt_pk_bf16_f32 v25, v26, v27
	v_cvt_pk_bf16_f32 v26, v28, v29
	v_cvt_pk_bf16_f32 v27, v30, v31
	v_pk_mul_f32 v[8:9], v[128:129], v[8:9] op_sel_hi:[0,1]
	v_pk_mul_f32 v[10:11], v[128:129], v[10:11] op_sel_hi:[0,1]
	v_pk_mul_f32 v[12:13], v[128:129], v[12:13] op_sel_hi:[0,1]
	v_pk_mul_f32 v[14:15], v[128:129], v[14:15] op_sel_hi:[0,1]
	v_cvt_pk_bf16_f32 v8, v8, v9
	v_cvt_pk_bf16_f32 v9, v10, v11
	v_cvt_pk_bf16_f32 v10, v12, v13
	v_cvt_pk_bf16_f32 v11, v14, v15
	s_nop 1
	s_add_i32 s45, s45, s94
	s_add_i32 s30, s30, s31
	s_add_i32 s33, s33, s34
	s_cmpk_gt_i32 s45, 0xff
	v_permlane32_swap_b32_e32 v56, v58
	v_permlane32_swap_b32_e32 v57, v59
	global_store_dwordx4 v[130:131], v[56:59], off offset:288
	v_permlane32_swap_b32_e32 v40, v42
	v_permlane32_swap_b32_e32 v41, v43
	global_store_dwordx4 v[130:131], v[40:43], off offset:352
	v_permlane32_swap_b32_e32 v24, v26
	v_permlane32_swap_b32_e32 v25, v27
	global_store_dwordx4 v[130:131], v[24:27], off offset:416
	v_permlane32_swap_b32_e32 v8, v10
	v_permlane32_swap_b32_e32 v9, v11
	global_store_dwordx4 v[130:131], v[8:11], off offset:480
	s_barrier
	s_cbranch_scc0 .LBB0_1672
